# MLP hidden buffer row pitch padded 8192->8448 B in both layers (up-proj stores, down-proj A loads)
# speedup vs baseline: 1.0285x; 1.0069x over previous
.LBB0_1000:
	s_sext_i32_i8 s77, s8
	s_add_u32 s8, s18, 0xc400000
	s_mov_b64 s[10:11], 0x80
	s_addc_u32 s9, s19, 0
	s_and_b32 s1, s1, 3
	s_add_i32 m0, s60, 0x18000
	v_lshl_add_u64 v[6:7], v[6:7], 0, s[10:11]
	s_lshl_b32 s13, s0, 13
	s_lshl_b32 s20, s1, 12
	s_waitcnt vmcnt(2)
	s_barrier
	global_load_lds_dwordx4 v[6:7], off
	v_lshl_add_u64 v[4:5], v[4:5], 0, s[10:11]
	s_add_i32 m0, s60, 0x1a000
	s_add_i32 s65, s60, 0x8000
	s_add_i32 s66, s60, 0xa000
	global_load_lds_dwordx4 v[4:5], off
	v_lshl_add_u64 v[0:1], v[0:1], 0, s[10:11]
	s_mov_b32 m0, s65
	s_add_u32 s6, s6, 0x40080
	global_load_lds_dwordx4 v[0:1], off
	v_lshl_add_u64 v[0:1], v[2:3], 0, s[10:11]
	s_mov_b32 m0, s66
	s_addc_u32 s7, s7, 0
	global_load_lds_dwordx4 v[0:1], off
	s_add_i32 m0, s60, 0x1c000
	v_lshl_add_u64 v[0:1], s[6:7], 0, v[132:133]
	global_load_lds_dwordx4 v[0:1], off
	v_lshl_add_u64 v[0:1], s[6:7], 0, v[134:135]
	s_add_i32 m0, s60, 0x1e000
	s_waitcnt vmcnt(0)
	v_lshrrev_b32_e32 v12, 4, v170
	global_load_lds_dwordx4 v[0:1], off
	v_and_b32_e32 v13, 15, v170
	v_and_b32_e32 v12, 3, v12
	v_lshlrev_b32_e32 v1, 4, v12
	v_lshlrev_b32_e32 v3, 2, v13
	v_lshl_or_b32 v2, v13, 6, v1
	v_and_b32_e32 v4, 32, v3
	v_bitop3_b32 v2, v2, s13, v4 bitop3:0xde
	v_lshlrev_b32_e32 v4, 6, v170
	s_movk_i32 s6, 0x3c0
	v_and_or_b32 v1, v4, s6, v1
	v_lshlrev_b32_e32 v4, 2, v170
	s_cmpk_lt_u32 s12, 0x100
	v_and_b32_e32 v4, 32, v4
	s_cselect_b64 s[12:13], -1, 0
	s_cmp_eq_u32 s1, 0
	v_lshl_or_b32 v150, s0, 6, v13
	v_bitop3_b32 v151, s20, v1, v4 bitop3:0xf6
	s_cselect_b64 s[20:21], -1, 0
	s_lshl_b32 s0, s0, 8
	v_lshlrev_b32_e32 v0, 3, v12
	s_add_i32 s0, s0, 0
	s_add_i32 s0, s0, 0x20000
	v_lshl_or_b32 v153, s1, 5, v0
	v_lshlrev_b32_e32 v0, 4, v11
	v_add_u32_e32 v152, s0, v3
	v_and_b32_e32 v0, 0x78000, v0
	v_lshlrev_b32_e32 v3, 11, v10
	v_or3_b32 v0, v8, v0, v3
	v_add_u32_e32 v0, v0, v9
	v_mov_b32_e32 v1, v133
	s_mov_b64 s[6:7], 0x40080
	v_lshl_add_u64 v[0:1], s[16:17], 0, v[0:1]
	v_lshl_add_u64 v[138:139], v[0:1], 0, s[6:7]
	v_lshlrev_b32_e32 v0, 8, v170
	v_cmp_gt_u32_e32 vcc, 2, v12
	v_and_b32_e32 v0, 0x38000, v0
	s_and_b64 s[20:21], s[20:21], vcc
	v_or3_b32 v0, v8, v0, v3
	s_waitcnt vmcnt(6)
	v_add_u32_e32 v0, v0, v9
	v_mov_b32_e32 v1, v133
	s_add_u32 s67, s18, 0xa00100
	v_lshl_add_u64 v[0:1], s[16:17], 0, v[0:1]
	s_addc_u32 s68, s19, 0
	s_add_i32 s69, 0, 0x10000
	s_add_i32 s72, 0, 0x14000
	v_lshlrev_b32_e32 v136, 5, v12
	v_mov_b32_e32 v137, v133
	v_lshl_add_u64 v[140:141], v[0:1], 0, s[6:7]
	v_mov_b64_e32 v[142:143], 0x800
	v_mov_b64_e32 v[144:145], 0x7ff
	s_mov_b64 s[18:19], 0x100
	v_add_u32_e32 v154, s69, v151
	v_add_u32_e32 v155, s72, v151
	v_add_u32_e32 v156, 0, v2
	s_mov_b64 s[22:23], 0x108000
	s_mov_b64 s[24:25], 0x108100
	s_mov_b64 s[26:27], 0x129000
	s_mov_b64 s[28:29], 0x129100
	s_mov_b64 s[30:31], 0x14a000
	s_mov_b64 s[34:35], 0x14a100
	s_mov_b64 s[36:37], 0x16b000
	s_mov_b64 s[38:39], 0x16b100
	s_mov_b64 s[40:41], 0x2000
	s_mov_b64 s[42:43], 0x2400
	s_mov_b64 s[44:45], 0x2800
	s_mov_b64 s[46:47], 0x2c00
	s_barrier
	s_branch .LBB0_1003

.LBB0_1013:
	s_cmp_eq_u32 s77, -1
	v_lshl_add_u32 v146, s50, 8, v150
	s_cbranch_scc1 .LBB0_1016
	v_lshl_add_u32 v157, s76, 10, v152
	ds_read_b32 v162, v157
	v_lshl_or_b32 v148, s77, 8, v153
	v_ashrrev_i32_e32 v147, 31, v146
	v_ashrrev_i32_e32 v149, 31, v148
	v_mul_u32_u24_e32 v158, 0x2100, v146
	v_mov_b32_e32 v159, 0
	v_lshl_add_u64 v[158:159], s[8:9], 0, v[158:159]
	v_lshlrev_b64 v[164:165], 1, v[148:149]
	s_waitcnt lgkmcnt(0)
	v_pk_mul_f32 v[172:173], v[64:65], v[162:163] op_sel_hi:[1,0]
	v_lshl_add_u64 v[148:149], v[158:159], 0, v[164:165]
	v_pk_mul_f32 v[158:159], v[70:71], v[162:163] op_sel_hi:[1,0]
	v_pk_mul_f32 v[160:161], v[68:69], v[162:163] op_sel_hi:[1,0]
	v_pk_mul_f32 v[166:167], v[66:67], v[162:163] op_sel_hi:[1,0]
	v_max_f32_e32 v163, 0, v173
	v_mul_f32_e32 v163, v163, v163
	v_max_f32_e32 v147, 0, v160
	v_max_f32_e32 v161, 0, v161
	v_max_f32_e32 v158, 0, v158
	v_pk_mul_f32 v[122:123], v[122:123], v[162:163] op_sel_hi:[1,0]
	v_pk_mul_f32 v[120:121], v[120:121], v[162:163] op_sel_hi:[1,0]
	v_max_f32_e32 v160, 0, v172
	v_mul_f32_e32 v147, v147, v147
	v_mul_f32_e32 v161, v161, v161
	v_max_f32_e32 v166, 0, v166
	v_mul_f32_e32 v171, v158, v158
	v_max_f32_e32 v158, 0, v159
	v_max_f32_e32 v159, 0, v167
	v_pk_mul_f32 v[126:127], v[126:127], v[162:163] op_sel_hi:[1,0]
	v_pk_mul_f32 v[124:125], v[124:125], v[162:163] op_sel_hi:[1,0]
	v_max_f32_e32 v120, 0, v120
	v_max_f32_e32 v121, 0, v121
	v_max_f32_e32 v122, 0, v122
	v_mul_f32_e32 v160, v160, v160
	v_mul_f32_e32 v166, v166, v166
	v_mul_f32_e32 v167, v158, v158
	v_mul_f32_e32 v172, v159, v159
	v_cvt_pk_bf16_f32 v158, v147, v161
	v_max_f32_e32 v124, 0, v124
	v_mul_f32_e32 v147, v120, v120
	v_max_f32_e32 v120, 0, v125
	v_mul_f32_e32 v125, v121, v121
	v_max_f32_e32 v121, 0, v126
	v_mul_f32_e32 v126, v122, v122
	v_max_f32_e32 v122, 0, v127
	v_max_f32_e32 v123, 0, v123
	v_cvt_pk_bf16_f32 v159, v171, v167
	v_cvt_pk_bf16_f32 v160, v160, v163
	v_cvt_pk_bf16_f32 v161, v166, v172
	global_store_dwordx4 v[148:149], v[158:161], off sc1 nt
	s_nop 1
	v_mul_f32_e32 v124, v124, v124
	v_mul_f32_e32 v120, v120, v120
	v_mul_f32_e32 v121, v121, v121
	v_mul_f32_e32 v122, v122, v122
	v_mul_f32_e32 v123, v123, v123
	v_cvt_pk_bf16_f32 v120, v124, v120
	v_cvt_pk_bf16_f32 v121, v121, v122
	v_cvt_pk_bf16_f32 v122, v147, v125
	v_cvt_pk_bf16_f32 v123, v126, v123
	v_lshl_add_u64 v[124:125], v[148:149], 0, s[18:19]
	global_store_dwordx4 v[124:125], v[120:123], off sc1 nt
	s_nop 1
	ds_read_b32 v124, v157 offset:64
	v_or_b32_e32 v120, 16, v146
	v_ashrrev_i32_e32 v121, 31, v120
	v_mul_u32_u24_e32 v120, 0x2100, v120
	v_mov_b32_e32 v121, 0
	v_lshl_add_u64 v[120:121], s[8:9], 0, v[120:121]
	s_waitcnt lgkmcnt(0)
	v_pk_mul_f32 v[160:161], v[56:57], v[124:125] op_sel_hi:[1,0]
	v_lshl_add_u64 v[126:127], v[120:121], 0, v[164:165]
	v_pk_mul_f32 v[120:121], v[62:63], v[124:125] op_sel_hi:[1,0]
	v_pk_mul_f32 v[122:123], v[60:61], v[124:125] op_sel_hi:[1,0]
	v_pk_mul_f32 v[158:159], v[58:59], v[124:125] op_sel_hi:[1,0]
	v_max_f32_e32 v125, 0, v160
	v_max_f32_e32 v122, 0, v122
	v_mul_f32_e32 v125, v125, v125
	v_max_f32_e32 v123, 0, v123
	v_max_f32_e32 v120, 0, v120
	v_mul_f32_e32 v122, v122, v122
	v_max_f32_e32 v147, 0, v161
	v_mul_f32_e32 v123, v123, v123
	v_max_f32_e32 v158, 0, v158
	v_mul_f32_e32 v160, v120, v120
	v_max_f32_e32 v120, 0, v121
	v_max_f32_e32 v121, 0, v159
	v_pk_mul_f32 v[114:115], v[114:115], v[124:125] op_sel_hi:[1,0]
	v_pk_mul_f32 v[112:113], v[112:113], v[124:125] op_sel_hi:[1,0]
	v_mul_f32_e32 v147, v147, v147
	v_mul_f32_e32 v158, v158, v158
	v_mul_f32_e32 v159, v120, v120
	v_mul_f32_e32 v161, v121, v121
	v_cvt_pk_bf16_f32 v120, v122, v123
	v_pk_mul_f32 v[118:119], v[118:119], v[124:125] op_sel_hi:[1,0]
	v_pk_mul_f32 v[116:117], v[116:117], v[124:125] op_sel_hi:[1,0]
	v_max_f32_e32 v112, 0, v112
	v_max_f32_e32 v113, 0, v113
	v_max_f32_e32 v114, 0, v114
	v_cvt_pk_bf16_f32 v121, v160, v159
	v_cvt_pk_bf16_f32 v122, v125, v147
	v_cvt_pk_bf16_f32 v123, v158, v161
	global_store_dwordx4 v[126:127], v[120:123], off sc1 nt
	s_nop 1
	v_max_f32_e32 v116, 0, v116
	v_mul_f32_e32 v120, v112, v112
	v_max_f32_e32 v112, 0, v117
	v_mul_f32_e32 v117, v113, v113
	v_max_f32_e32 v113, 0, v118
	v_mul_f32_e32 v118, v114, v114
	v_max_f32_e32 v114, 0, v119
	v_max_f32_e32 v115, 0, v115
	v_mul_f32_e32 v116, v116, v116
	v_mul_f32_e32 v112, v112, v112
	v_mul_f32_e32 v113, v113, v113
	v_mul_f32_e32 v114, v114, v114
	v_mul_f32_e32 v115, v115, v115
	v_cvt_pk_bf16_f32 v112, v116, v112
	v_cvt_pk_bf16_f32 v113, v113, v114
	v_cvt_pk_bf16_f32 v114, v120, v117
	v_cvt_pk_bf16_f32 v115, v118, v115
	v_lshl_add_u64 v[116:117], v[126:127], 0, s[18:19]
	global_store_dwordx4 v[116:117], v[112:115], off sc1 nt
	s_nop 1
	ds_read_b32 v116, v157 offset:128
	v_or_b32_e32 v112, 32, v146
	v_ashrrev_i32_e32 v113, 31, v112
	v_mul_u32_u24_e32 v112, 0x2100, v112
	v_mov_b32_e32 v113, 0
	v_lshl_add_u64 v[112:113], s[8:9], 0, v[112:113]
	s_waitcnt lgkmcnt(0)
	v_pk_mul_f32 v[122:123], v[40:41], v[116:117] op_sel_hi:[1,0]
	v_lshl_add_u64 v[118:119], v[112:113], 0, v[164:165]
	v_pk_mul_f32 v[112:113], v[50:51], v[116:117] op_sel_hi:[1,0]
	v_pk_mul_f32 v[114:115], v[48:49], v[116:117] op_sel_hi:[1,0]
	v_pk_mul_f32 v[120:121], v[42:43], v[116:117] op_sel_hi:[1,0]
	v_max_f32_e32 v117, 0, v122
	v_max_f32_e32 v114, 0, v114
	v_mul_f32_e32 v117, v117, v117
	v_max_f32_e32 v115, 0, v115
	v_max_f32_e32 v112, 0, v112
	v_mul_f32_e32 v114, v114, v114
	v_max_f32_e32 v122, 0, v123
	v_mul_f32_e32 v115, v115, v115
	v_max_f32_e32 v120, 0, v120
	v_mul_f32_e32 v123, v112, v112
	v_max_f32_e32 v112, 0, v113
	v_max_f32_e32 v113, 0, v121
	v_pk_mul_f32 v[106:107], v[106:107], v[116:117] op_sel_hi:[1,0]
	v_pk_mul_f32 v[104:105], v[104:105], v[116:117] op_sel_hi:[1,0]
	v_mul_f32_e32 v122, v122, v122
	v_mul_f32_e32 v120, v120, v120
	v_mul_f32_e32 v121, v112, v112
	v_mul_f32_e32 v124, v113, v113
	v_cvt_pk_bf16_f32 v112, v114, v115
	v_pk_mul_f32 v[110:111], v[110:111], v[116:117] op_sel_hi:[1,0]
	v_pk_mul_f32 v[108:109], v[108:109], v[116:117] op_sel_hi:[1,0]
	v_max_f32_e32 v104, 0, v104
	v_max_f32_e32 v105, 0, v105
	v_max_f32_e32 v106, 0, v106
	v_cvt_pk_bf16_f32 v113, v123, v121
	v_cvt_pk_bf16_f32 v114, v117, v122
	v_cvt_pk_bf16_f32 v115, v120, v124
	global_store_dwordx4 v[118:119], v[112:115], off sc1 nt
	s_nop 1
	v_max_f32_e32 v108, 0, v108
	v_mul_f32_e32 v112, v104, v104
	v_max_f32_e32 v104, 0, v109
	v_mul_f32_e32 v109, v105, v105
	v_max_f32_e32 v105, 0, v110
	v_mul_f32_e32 v110, v106, v106
	v_max_f32_e32 v106, 0, v111
	v_max_f32_e32 v107, 0, v107
	v_mul_f32_e32 v108, v108, v108
	v_mul_f32_e32 v104, v104, v104
	v_mul_f32_e32 v105, v105, v105
	v_mul_f32_e32 v106, v106, v106
	v_mul_f32_e32 v107, v107, v107
	v_cvt_pk_bf16_f32 v104, v108, v104
	v_cvt_pk_bf16_f32 v105, v105, v106
	v_cvt_pk_bf16_f32 v106, v112, v109
	v_cvt_pk_bf16_f32 v107, v110, v107
	v_lshl_add_u64 v[108:109], v[118:119], 0, s[18:19]
	global_store_dwordx4 v[108:109], v[104:107], off sc1 nt
	s_nop 1
	ds_read_b32 v108, v157 offset:192
	v_or_b32_e32 v104, 48, v146
	v_ashrrev_i32_e32 v105, 31, v104
	v_mul_u32_u24_e32 v104, 0x2100, v104
	v_mov_b32_e32 v105, 0
	v_lshl_add_u64 v[104:105], s[8:9], 0, v[104:105]
	s_waitcnt lgkmcnt(0)
	v_pk_mul_f32 v[114:115], v[32:33], v[108:109] op_sel_hi:[1,0]
	v_lshl_add_u64 v[110:111], v[104:105], 0, v[164:165]
	v_pk_mul_f32 v[104:105], v[38:39], v[108:109] op_sel_hi:[1,0]
	v_pk_mul_f32 v[106:107], v[36:37], v[108:109] op_sel_hi:[1,0]
	v_pk_mul_f32 v[112:113], v[34:35], v[108:109] op_sel_hi:[1,0]
	v_max_f32_e32 v109, 0, v114
	v_max_f32_e32 v106, 0, v106
	v_mul_f32_e32 v109, v109, v109
	v_max_f32_e32 v107, 0, v107
	v_max_f32_e32 v104, 0, v104
	v_mul_f32_e32 v106, v106, v106
	v_max_f32_e32 v114, 0, v115
	v_mul_f32_e32 v107, v107, v107
	v_max_f32_e32 v112, 0, v112
	v_mul_f32_e32 v115, v104, v104
	v_max_f32_e32 v104, 0, v105
	v_max_f32_e32 v105, 0, v113
	v_pk_mul_f32 v[98:99], v[98:99], v[108:109] op_sel_hi:[1,0]
	v_pk_mul_f32 v[96:97], v[96:97], v[108:109] op_sel_hi:[1,0]
	v_mul_f32_e32 v114, v114, v114
	v_mul_f32_e32 v112, v112, v112
	v_mul_f32_e32 v113, v104, v104
	v_mul_f32_e32 v116, v105, v105
	v_cvt_pk_bf16_f32 v104, v106, v107
	v_pk_mul_f32 v[102:103], v[102:103], v[108:109] op_sel_hi:[1,0]
	v_pk_mul_f32 v[100:101], v[100:101], v[108:109] op_sel_hi:[1,0]
	v_max_f32_e32 v96, 0, v96
	v_max_f32_e32 v97, 0, v97
	v_max_f32_e32 v98, 0, v98
	v_cvt_pk_bf16_f32 v105, v115, v113
	v_cvt_pk_bf16_f32 v106, v109, v114
	v_cvt_pk_bf16_f32 v107, v112, v116
	global_store_dwordx4 v[110:111], v[104:107], off sc1 nt
	s_nop 1
	v_max_f32_e32 v100, 0, v100
	v_mul_f32_e32 v104, v96, v96
	v_max_f32_e32 v96, 0, v101
	v_mul_f32_e32 v101, v97, v97
	v_max_f32_e32 v97, 0, v102
	v_mul_f32_e32 v102, v98, v98
	v_max_f32_e32 v98, 0, v103
	v_max_f32_e32 v99, 0, v99
	v_mul_f32_e32 v100, v100, v100
	v_mul_f32_e32 v96, v96, v96
	v_mul_f32_e32 v97, v97, v97
	v_mul_f32_e32 v98, v98, v98
	v_mul_f32_e32 v99, v99, v99
	v_cvt_pk_bf16_f32 v96, v100, v96
	v_cvt_pk_bf16_f32 v97, v97, v98
	v_cvt_pk_bf16_f32 v98, v104, v101
	v_cvt_pk_bf16_f32 v99, v102, v99
	v_lshl_add_u64 v[100:101], v[110:111], 0, s[18:19]
	global_store_dwordx4 v[100:101], v[96:99], off sc1 nt
	s_nop 1
	ds_read_b32 v100, v157 offset:512
	v_lshl_add_u64 v[102:103], v[148:149], 0, s[22:23]
	s_waitcnt lgkmcnt(0)
	v_pk_mul_f32 v[106:107], v[24:25], v[100:101] op_sel_hi:[1,0]
	v_pk_mul_f32 v[96:97], v[30:31], v[100:101] op_sel_hi:[1,0]
	v_pk_mul_f32 v[98:99], v[28:29], v[100:101] op_sel_hi:[1,0]
	v_pk_mul_f32 v[104:105], v[26:27], v[100:101] op_sel_hi:[1,0]
	v_max_f32_e32 v101, 0, v106
	v_max_f32_e32 v98, 0, v98
	v_mul_f32_e32 v101, v101, v101
	v_max_f32_e32 v99, 0, v99
	v_max_f32_e32 v96, 0, v96
	v_mul_f32_e32 v98, v98, v98
	v_max_f32_e32 v106, 0, v107
	v_mul_f32_e32 v99, v99, v99
	v_max_f32_e32 v104, 0, v104
	v_mul_f32_e32 v107, v96, v96
	v_max_f32_e32 v96, 0, v97
	v_max_f32_e32 v97, 0, v105
	v_pk_mul_f32 v[90:91], v[90:91], v[100:101] op_sel_hi:[1,0]
	v_pk_mul_f32 v[88:89], v[88:89], v[100:101] op_sel_hi:[1,0]
	v_mul_f32_e32 v106, v106, v106
	v_mul_f32_e32 v104, v104, v104
	v_mul_f32_e32 v105, v96, v96
	v_mul_f32_e32 v108, v97, v97
	v_cvt_pk_bf16_f32 v96, v98, v99
	v_pk_mul_f32 v[94:95], v[94:95], v[100:101] op_sel_hi:[1,0]
	v_pk_mul_f32 v[92:93], v[92:93], v[100:101] op_sel_hi:[1,0]
	v_max_f32_e32 v88, 0, v88
	v_max_f32_e32 v89, 0, v89
	v_max_f32_e32 v90, 0, v90
	v_cvt_pk_bf16_f32 v97, v107, v105
	v_cvt_pk_bf16_f32 v98, v101, v106
	v_cvt_pk_bf16_f32 v99, v104, v108
	global_store_dwordx4 v[102:103], v[96:99], off sc1 nt
	s_nop 1
	v_max_f32_e32 v92, 0, v92
	v_mul_f32_e32 v96, v88, v88
	v_max_f32_e32 v88, 0, v93
	v_mul_f32_e32 v93, v89, v89
	v_max_f32_e32 v89, 0, v94
	v_mul_f32_e32 v94, v90, v90
	v_max_f32_e32 v90, 0, v95
	v_max_f32_e32 v91, 0, v91
	v_mul_f32_e32 v92, v92, v92
	v_mul_f32_e32 v88, v88, v88
	v_mul_f32_e32 v89, v89, v89
	v_mul_f32_e32 v90, v90, v90
	v_mul_f32_e32 v91, v91, v91
	v_cvt_pk_bf16_f32 v88, v92, v88
	v_cvt_pk_bf16_f32 v89, v89, v90
	v_cvt_pk_bf16_f32 v90, v96, v93
	v_cvt_pk_bf16_f32 v91, v94, v91
	v_lshl_add_u64 v[92:93], v[148:149], 0, s[24:25]
	global_store_dwordx4 v[92:93], v[88:91], off sc1 nt
	s_nop 1
	ds_read_b32 v92, v157 offset:576
	v_lshl_add_u64 v[94:95], v[148:149], 0, s[26:27]
	s_waitcnt lgkmcnt(0)
	v_pk_mul_f32 v[98:99], v[16:17], v[92:93] op_sel_hi:[1,0]
	v_pk_mul_f32 v[88:89], v[22:23], v[92:93] op_sel_hi:[1,0]
	v_pk_mul_f32 v[90:91], v[20:21], v[92:93] op_sel_hi:[1,0]
	v_pk_mul_f32 v[96:97], v[18:19], v[92:93] op_sel_hi:[1,0]
	v_max_f32_e32 v93, 0, v98
	v_max_f32_e32 v90, 0, v90
	v_mul_f32_e32 v93, v93, v93
	v_max_f32_e32 v91, 0, v91
	v_max_f32_e32 v88, 0, v88
	v_mul_f32_e32 v90, v90, v90
	v_max_f32_e32 v98, 0, v99
	v_mul_f32_e32 v91, v91, v91
	v_max_f32_e32 v96, 0, v96
	v_mul_f32_e32 v99, v88, v88
	v_max_f32_e32 v88, 0, v89
	v_max_f32_e32 v89, 0, v97
	v_pk_mul_f32 v[82:83], v[82:83], v[92:93] op_sel_hi:[1,0]
	v_pk_mul_f32 v[80:81], v[80:81], v[92:93] op_sel_hi:[1,0]
	v_mul_f32_e32 v98, v98, v98
	v_mul_f32_e32 v96, v96, v96
	v_mul_f32_e32 v97, v88, v88
	v_mul_f32_e32 v100, v89, v89
	v_cvt_pk_bf16_f32 v88, v90, v91
	v_pk_mul_f32 v[86:87], v[86:87], v[92:93] op_sel_hi:[1,0]
	v_pk_mul_f32 v[84:85], v[84:85], v[92:93] op_sel_hi:[1,0]
	v_max_f32_e32 v80, 0, v80
	v_max_f32_e32 v81, 0, v81
	v_max_f32_e32 v82, 0, v82
	v_cvt_pk_bf16_f32 v89, v99, v97
	v_cvt_pk_bf16_f32 v90, v93, v98
	v_cvt_pk_bf16_f32 v91, v96, v100
	global_store_dwordx4 v[94:95], v[88:91], off sc1 nt
	s_nop 1
	v_max_f32_e32 v84, 0, v84
	v_mul_f32_e32 v88, v80, v80
	v_max_f32_e32 v80, 0, v85
	v_mul_f32_e32 v85, v81, v81
	v_max_f32_e32 v81, 0, v86
	v_mul_f32_e32 v86, v82, v82
	v_max_f32_e32 v82, 0, v87
	v_max_f32_e32 v83, 0, v83
	v_mul_f32_e32 v84, v84, v84
	v_mul_f32_e32 v80, v80, v80
	v_mul_f32_e32 v81, v81, v81
	v_mul_f32_e32 v82, v82, v82
	v_mul_f32_e32 v83, v83, v83
	v_cvt_pk_bf16_f32 v80, v84, v80
	v_cvt_pk_bf16_f32 v81, v81, v82
	v_cvt_pk_bf16_f32 v82, v88, v85
	v_cvt_pk_bf16_f32 v83, v86, v83
	v_lshl_add_u64 v[84:85], v[148:149], 0, s[28:29]
	global_store_dwordx4 v[84:85], v[80:83], off sc1 nt
	s_nop 1
	ds_read_b32 v84, v157 offset:640
	v_lshl_add_u64 v[86:87], v[148:149], 0, s[30:31]
	s_waitcnt lgkmcnt(0)
	v_pk_mul_f32 v[90:91], v[8:9], v[84:85] op_sel_hi:[1,0]
	v_pk_mul_f32 v[80:81], v[14:15], v[84:85] op_sel_hi:[1,0]
	v_pk_mul_f32 v[82:83], v[12:13], v[84:85] op_sel_hi:[1,0]
	v_pk_mul_f32 v[88:89], v[10:11], v[84:85] op_sel_hi:[1,0]
	v_max_f32_e32 v85, 0, v90
	v_max_f32_e32 v82, 0, v82
	v_mul_f32_e32 v85, v85, v85
	v_max_f32_e32 v83, 0, v83
	v_max_f32_e32 v80, 0, v80
	v_mul_f32_e32 v82, v82, v82
	v_max_f32_e32 v90, 0, v91
	v_mul_f32_e32 v83, v83, v83
	v_max_f32_e32 v88, 0, v88
	v_mul_f32_e32 v91, v80, v80
	v_max_f32_e32 v80, 0, v81
	v_max_f32_e32 v81, 0, v89
	v_pk_mul_f32 v[74:75], v[74:75], v[84:85] op_sel_hi:[1,0]
	v_pk_mul_f32 v[72:73], v[72:73], v[84:85] op_sel_hi:[1,0]
	v_mul_f32_e32 v90, v90, v90
	v_mul_f32_e32 v88, v88, v88
	v_mul_f32_e32 v89, v80, v80
	v_mul_f32_e32 v92, v81, v81
	v_cvt_pk_bf16_f32 v80, v82, v83
	v_pk_mul_f32 v[78:79], v[78:79], v[84:85] op_sel_hi:[1,0]
	v_pk_mul_f32 v[76:77], v[76:77], v[84:85] op_sel_hi:[1,0]
	v_max_f32_e32 v72, 0, v72
	v_max_f32_e32 v73, 0, v73
	v_max_f32_e32 v74, 0, v74
	v_cvt_pk_bf16_f32 v81, v91, v89
	v_cvt_pk_bf16_f32 v82, v85, v90
	v_cvt_pk_bf16_f32 v83, v88, v92
	global_store_dwordx4 v[86:87], v[80:83], off sc1 nt
	s_nop 1
	v_max_f32_e32 v76, 0, v76
	v_mul_f32_e32 v80, v72, v72
	v_max_f32_e32 v72, 0, v77
	v_mul_f32_e32 v77, v73, v73
	v_max_f32_e32 v73, 0, v78
	v_mul_f32_e32 v78, v74, v74
	v_max_f32_e32 v74, 0, v79
	v_max_f32_e32 v75, 0, v75
	v_mul_f32_e32 v76, v76, v76
	v_mul_f32_e32 v72, v72, v72
	v_mul_f32_e32 v73, v73, v73
	v_mul_f32_e32 v74, v74, v74
	v_mul_f32_e32 v75, v75, v75
	v_cvt_pk_bf16_f32 v72, v76, v72
	v_cvt_pk_bf16_f32 v73, v73, v74
	v_cvt_pk_bf16_f32 v74, v80, v77
	v_cvt_pk_bf16_f32 v75, v78, v75
	v_lshl_add_u64 v[76:77], v[148:149], 0, s[34:35]
	global_store_dwordx4 v[76:77], v[72:75], off sc1 nt
	s_nop 1
	ds_read_b32 v76, v157 offset:704
	v_lshl_add_u64 v[78:79], v[148:149], 0, s[36:37]
	s_waitcnt lgkmcnt(0)
	v_pk_mul_f32 v[82:83], v[0:1], v[76:77] op_sel_hi:[1,0]
	v_pk_mul_f32 v[72:73], v[6:7], v[76:77] op_sel_hi:[1,0]
	v_pk_mul_f32 v[74:75], v[4:5], v[76:77] op_sel_hi:[1,0]
	v_pk_mul_f32 v[80:81], v[2:3], v[76:77] op_sel_hi:[1,0]
	v_max_f32_e32 v77, 0, v82
	v_max_f32_e32 v74, 0, v74
	v_mul_f32_e32 v77, v77, v77
	v_max_f32_e32 v75, 0, v75
	v_max_f32_e32 v72, 0, v72
	v_mul_f32_e32 v74, v74, v74
	v_max_f32_e32 v82, 0, v83
	v_mul_f32_e32 v75, v75, v75
	v_max_f32_e32 v80, 0, v80
	v_mul_f32_e32 v83, v72, v72
	v_max_f32_e32 v72, 0, v73
	v_max_f32_e32 v73, 0, v81
	v_pk_mul_f32 v[46:47], v[46:47], v[76:77] op_sel_hi:[1,0]
	v_pk_mul_f32 v[44:45], v[44:45], v[76:77] op_sel_hi:[1,0]
	v_mul_f32_e32 v82, v82, v82
	v_mul_f32_e32 v80, v80, v80
	v_mul_f32_e32 v81, v72, v72
	v_mul_f32_e32 v84, v73, v73
	v_cvt_pk_bf16_f32 v72, v74, v75
	v_pk_mul_f32 v[54:55], v[54:55], v[76:77] op_sel_hi:[1,0]
	v_pk_mul_f32 v[52:53], v[52:53], v[76:77] op_sel_hi:[1,0]
	v_max_f32_e32 v44, 0, v44
	v_max_f32_e32 v45, 0, v45
	v_max_f32_e32 v46, 0, v46
	v_cvt_pk_bf16_f32 v73, v83, v81
	v_cvt_pk_bf16_f32 v74, v77, v82
	v_cvt_pk_bf16_f32 v75, v80, v84
	global_store_dwordx4 v[78:79], v[72:75], off sc1 nt
	s_nop 1
	v_max_f32_e32 v52, 0, v52
	v_mul_f32_e32 v72, v44, v44
	v_max_f32_e32 v44, 0, v53
	v_mul_f32_e32 v53, v45, v45
	v_max_f32_e32 v45, 0, v54
	v_mul_f32_e32 v54, v46, v46
	v_max_f32_e32 v46, 0, v55
	v_max_f32_e32 v47, 0, v47
	v_mul_f32_e32 v52, v52, v52
	v_mul_f32_e32 v44, v44, v44
	v_mul_f32_e32 v45, v45, v45
	v_mul_f32_e32 v46, v46, v46
	v_mul_f32_e32 v47, v47, v47
	v_cvt_pk_bf16_f32 v44, v52, v44
	v_cvt_pk_bf16_f32 v45, v45, v46
	v_cvt_pk_bf16_f32 v46, v72, v53
	v_cvt_pk_bf16_f32 v47, v54, v47
	v_lshl_add_u64 v[52:53], v[148:149], 0, s[38:39]
	global_store_dwordx4 v[52:53], v[44:47], off sc1 nt
	s_nop 1
	s_cbranch_execz .LBB0_1017
	s_andn2_b64 vcc, exec, s[6:7]
	s_mov_b64 s[0:1], -1
	s_cbranch_vccnz .LBB0_1002
	s_branch .LBB0_1020

.LBB0_1082:
	s_ashr_i32 s5, s5, 3
	s_waitcnt lgkmcnt(0)
	s_add_u32 s31, s14, 0x1200000
	s_addc_u32 s33, s15, 0
	s_add_u32 s34, s14, 0xc400000
	s_addc_u32 s35, s15, 0
	s_add_i32 s4, s4, s5
	s_ashr_i32 s5, s4, 31
	s_lshr_b32 s5, s5, 27
	s_add_i32 s5, s4, s5
	s_ashr_i32 s6, s5, 5
	s_andn2_b32 s5, s5, 31
	s_waitcnt vmcnt(0)
	v_lshlrev_b32_e32 v0, 4, v170
	v_and_b32_e32 v1, 32, v170
	s_sub_i32 s5, s4, s5
	v_bfe_u32 v10, v170, 2, 4
	v_bitop3_b32 v8, v0, v1, 48 bitop3:0x6c
	v_and_b32_e32 v9, 64, v170
	v_lshrrev_b32_e32 v2, 3, v170
	s_movk_i32 s0, 0x70
	v_add_u32_e32 v11, 0x2000, v0
	s_bfe_i32 s4, s5, 0x80000
	v_or_b32_e32 v1, v8, v9
	v_and_or_b32 v3, v2, s0, v10
	v_lshrrev_b32_e32 v0, 7, v11
	s_movk_i32 s0, 0xf0
	s_bfe_u32 s4, s4, 0x3000c
	v_mul_u32_u24_e32 v172, 0x2100, v3
	v_add_u32_e32 v172, v172, v1
	v_and_or_b32 v3, v0, s0, v10
	s_add_i32 s7, s5, s4
	v_mul_u32_u24_e32 v174, 0x2100, v3
	v_add_u32_e32 v174, v174, v1
	v_lshrrev_b32_e32 v3, 1, v170
	v_lshrrev_b32_e32 v4, 5, v170
	s_bfe_i32 s4, s7, 0x80000
	s_and_b32 s7, s7, 0xf8
	v_and_b32_e32 v3, 24, v3
	v_and_b32_e32 v4, 4, v4
	v_bfe_u32 v5, v170, 2, 2
	s_sext_i32_i16 s4, s4
	s_sub_i32 s5, s5, s7
	v_or3_b32 v3, v4, v5, v3
	s_movk_i32 s0, 0x60
	s_lshl_b32 s6, s6, 3
	s_lshr_b32 s4, s4, 3
	s_sext_i32_i8 s5, s5
	s_lshr_b32 s1, s8, 6
	v_and_or_b32 v2, v2, s0, v3
	s_movk_i32 s0, 0xe0
	s_add_i32 s24, s6, s5
	s_bfe_i64 s[6:7], s[4:5], 0x100000
	v_and_or_b32 v0, v0, s0, v3
	s_lshr_b32 s0, s8, 8
	s_lshl_b32 s36, s1, 10
	s_lshl_b64 s[26:27], s[6:7], 21
	s_add_u32 s6, s31, s26
	s_addc_u32 s7, s33, s27
	s_add_i32 s37, s36, 0
	v_lshl_or_b32 v176, v2, 13, v1
	s_add_i32 m0, s37, 0x10000
	v_lshl_or_b32 v178, v0, 13, v1
	global_load_lds_dwordx4 v176, s[6:7]
	s_add_i32 m0, s37, 0x12000
	s_add_u32 s10, s6, 0x100000
	global_load_lds_dwordx4 v178, s[6:7]
	s_addc_u32 s11, s7, 0
	s_add_i32 m0, s37, 0x14000
	s_ashr_i32 s25, s24, 31
	global_load_lds_dwordx4 v176, s[10:11]
	s_add_i32 m0, s37, 0x16000
	v_mov_b32_e32 v177, 0
	global_load_lds_dwordx4 v178, s[10:11]
	s_mul_i32 s10, s24, 0x210000
	s_mov_b32 s11, 0
	s_add_u32 s16, s34, s10
	s_addc_u32 s17, s35, s11
	s_add_i32 s38, s37, 0x2000
	s_mov_b32 m0, s37
	s_add_u32 s10, s16, 0x108000
	global_load_lds_dwordx4 v172, s[16:17]
	s_mov_b32 m0, s38
	s_addc_u32 s11, s17, 0
	s_add_i32 s39, s37, 0x4000
	global_load_lds_dwordx4 v174, s[16:17]
	s_mov_b32 m0, s39
	s_add_i32 s40, s37, 0x6000
	global_load_lds_dwordx4 v172, s[10:11]
	s_mov_b32 m0, s40
	v_mov_b32_e32 v179, v177
	global_load_lds_dwordx4 v174, s[10:11]
	v_mov_b32_e32 v173, v177
	v_mov_b32_e32 v175, v177
	s_cmp_eq_u32 s0, 1
	s_mov_b32 s5, 0
	v_lshl_add_u64 v[6:7], s[6:7], 0, v[176:177]
	v_lshl_add_u64 v[4:5], s[6:7], 0, v[178:179]
	v_lshl_add_u64 v[0:1], s[16:17], 0, v[172:173]
	s_cselect_b64 s[10:11], -1, 0
	s_cmp_lg_u32 s0, 1
	v_lshl_add_u64 v[2:3], s[16:17], 0, v[174:175]
	s_cbranch_scc1 .LBB0_1084
	s_barrier
.LBB0_1084:
	s_add_u32 s16, s14, 0x412a000
	s_mov_b64 s[18:19], 0x80
	s_addc_u32 s17, s15, 0
	s_and_b32 s41, s1, 3
	s_add_i32 m0, s37, 0x18000
	v_lshl_add_u64 v[6:7], v[6:7], 0, s[18:19]
	s_lshl_b32 s1, s0, 13
	s_lshl_b32 s9, s41, 12
	s_waitcnt vmcnt(2)
	s_barrier
	global_load_lds_dwordx4 v[6:7], off
	v_lshl_add_u64 v[4:5], v[4:5], 0, s[18:19]
	s_add_i32 m0, s37, 0x1a000
	s_add_i32 s42, s37, 0x8000
	s_add_i32 s43, s37, 0xa000
	global_load_lds_dwordx4 v[4:5], off
	v_lshl_add_u64 v[0:1], v[0:1], 0, s[18:19]
	s_mov_b32 m0, s42
	s_add_u32 s6, s6, 0x100080
	global_load_lds_dwordx4 v[0:1], off
	v_lshl_add_u64 v[0:1], v[2:3], 0, s[18:19]
	s_mov_b32 m0, s43
	s_addc_u32 s7, s7, 0
	global_load_lds_dwordx4 v[0:1], off
	s_add_i32 m0, s37, 0x1c000
	v_lshl_add_u64 v[0:1], s[6:7], 0, v[176:177]
	global_load_lds_dwordx4 v[0:1], off
	v_lshl_add_u64 v[0:1], s[6:7], 0, v[178:179]
	s_add_i32 m0, s37, 0x1e000
	v_lshlrev_b32_e32 v4, 2, v170
	global_load_lds_dwordx4 v[0:1], off
	v_bfe_u32 v0, v170, 4, 2
	v_and_b32_e32 v1, 15, v170
	v_lshlrev_b32_e32 v3, 4, v0
	v_lshl_or_b32 v171, s0, 6, v1
	v_lshlrev_b32_e32 v2, 3, v0
	v_lshl_or_b32 v1, v1, 6, v3
	v_and_b32_e32 v4, 32, v4
	v_cmp_eq_u32_e64 s[6:7], 0, v0
	v_lshlrev_b32_e32 v0, 6, v11
	v_bitop3_b32 v5, v1, s1, v4 bitop3:0xde
	v_lshlrev_b32_e32 v1, 6, v170
	s_movk_i32 s0, 0x3c0
	v_lshl_or_b32 v213, s41, 5, v2
	v_and_b32_e32 v0, 0x1e0000, v0
	v_lshlrev_b32_e32 v2, 13, v10
	v_and_or_b32 v1, v1, s0, v3
	v_or3_b32 v0, v8, v0, v2
	v_bitop3_b32 v212, s9, v1, v4 bitop3:0xf6
	v_mov_b32_e32 v0, v174
	v_mov_b32_e32 v1, v177
	v_lshl_add_u64 v[0:1], s[14:15], 0, v[0:1]
	s_mov_b64 s[0:1], 0xc508080
	v_lshl_add_u64 v[180:181], v[0:1], 0, s[0:1]
	v_lshlrev_b32_e32 v0, 10, v170
	v_and_b32_e32 v0, 0xe0000, v0
	v_or3_b32 v0, v8, v0, v2
	s_cmpk_lt_u32 s8, 0x100
	v_mov_b32_e32 v0, v172
	v_mov_b32_e32 v1, v177
	s_waitcnt vmcnt(6)
	s_cselect_b64 s[20:21], -1, 0
	v_lshl_add_u64 v[0:1], s[14:15], 0, v[0:1]
	s_add_u32 s45, s14, 0x1200100
	v_lshl_add_u64 v[182:183], v[0:1], 0, s[0:1]
	s_addc_u32 s46, s15, 0
	s_add_i32 s48, 0, 0x10000
	s_add_i32 s49, 0, 0x14000
	v_mbcnt_lo_u32_b32 v0, -1, 0
	s_sext_i32_i8 s47, s4
	s_mov_b32 s44, s2
	v_mov_b64_e32 v[184:185], 0x200
	v_mov_b64_e32 v[186:187], 0x1ff
	v_add_u32_e32 v214, s48, v212
	v_add_u32_e32 v215, s49, v212
	v_add_u32_e32 v216, 0, v5
	s_mov_b64 s[14:15], 0x100
	v_mbcnt_hi_u32_b32 v217, -1, v0
	s_mov_b32 s50, 0
	s_barrier
	s_branch .LBB0_1087

.LBB0_1093:
	s_ashr_i32 s1, s0, 31
	s_lshl_b64 s[22:23], s[0:1], 21
	s_add_u32 s0, s31, s22
	s_addc_u32 s1, s33, s23
	s_ashr_i32 s25, s24, 31
	s_mul_i32 s28, s24, 0x210000
	s_mov_b32 s29, 0
	s_add_u32 s25, s45, s26
	v_mov_b32_e32 v0, 0
	v_lshl_add_u64 v[128:129], v[180:181], 0, s[28:29]
	v_lshl_add_u64 v[130:131], v[182:183], 0, s[28:29]
	s_addc_u32 s54, s46, s27
	s_mov_b32 s55, 0
	s_mov_b64 s[26:27], 0
	s_waitcnt lgkmcnt(0)
	v_mov_b32_e32 v1, v0
	v_mov_b32_e32 v2, v0
	v_mov_b32_e32 v3, v0
	v_mov_b32_e32 v4, v0
	v_mov_b32_e32 v5, v0
	v_mov_b32_e32 v6, v0
	v_mov_b32_e32 v7, v0
	v_mov_b32_e32 v16, v0
	v_mov_b32_e32 v17, v0
	v_mov_b32_e32 v18, v0
	v_mov_b32_e32 v19, v0
	v_mov_b32_e32 v20, v0
	v_mov_b32_e32 v21, v0
	v_mov_b32_e32 v22, v0
	v_mov_b32_e32 v23, v0
	v_mov_b32_e32 v32, v0
	v_mov_b32_e32 v33, v0
	v_mov_b32_e32 v34, v0
	v_mov_b32_e32 v35, v0
	v_mov_b32_e32 v36, v0
	v_mov_b32_e32 v37, v0
	v_mov_b32_e32 v38, v0
	v_mov_b32_e32 v39, v0
	v_mov_b32_e32 v48, v0
	v_mov_b32_e32 v49, v0
	v_mov_b32_e32 v50, v0
	v_mov_b32_e32 v51, v0
	v_mov_b32_e32 v52, v0
	v_mov_b32_e32 v53, v0
	v_mov_b32_e32 v54, v0
	v_mov_b32_e32 v55, v0
	v_mov_b32_e32 v8, v0
	v_mov_b32_e32 v9, v0
	v_mov_b32_e32 v10, v0
	v_mov_b32_e32 v11, v0
	v_mov_b32_e32 v12, v0
	v_mov_b32_e32 v13, v0
	v_mov_b32_e32 v14, v0
	v_mov_b32_e32 v15, v0
	v_mov_b32_e32 v24, v0
	v_mov_b32_e32 v25, v0
	v_mov_b32_e32 v26, v0
	v_mov_b32_e32 v27, v0
	v_mov_b32_e32 v28, v0
	v_mov_b32_e32 v29, v0
	v_mov_b32_e32 v30, v0
	v_mov_b32_e32 v31, v0
	v_mov_b32_e32 v40, v0
	v_mov_b32_e32 v41, v0
	v_mov_b32_e32 v42, v0
	v_mov_b32_e32 v43, v0
	v_mov_b32_e32 v44, v0
	v_mov_b32_e32 v45, v0
	v_mov_b32_e32 v46, v0
	v_mov_b32_e32 v47, v0
	v_mov_b32_e32 v56, v0
	v_mov_b32_e32 v57, v0
	v_mov_b32_e32 v58, v0
	v_mov_b32_e32 v59, v0
	v_mov_b32_e32 v60, v0
	v_mov_b32_e32 v61, v0
	v_mov_b32_e32 v62, v0
	v_mov_b32_e32 v63, v0
	v_mov_b32_e32 v64, v0
	v_mov_b32_e32 v65, v0
	v_mov_b32_e32 v66, v0
	v_mov_b32_e32 v67, v0
	v_mov_b32_e32 v68, v0
	v_mov_b32_e32 v69, v0
	v_mov_b32_e32 v70, v0
	v_mov_b32_e32 v71, v0
	v_mov_b32_e32 v80, v0
	v_mov_b32_e32 v81, v0
	v_mov_b32_e32 v82, v0
	v_mov_b32_e32 v83, v0
	v_mov_b32_e32 v84, v0
	v_mov_b32_e32 v85, v0
	v_mov_b32_e32 v86, v0
	v_mov_b32_e32 v87, v0
	v_mov_b32_e32 v96, v0
	v_mov_b32_e32 v97, v0
	v_mov_b32_e32 v98, v0
	v_mov_b32_e32 v99, v0
	v_mov_b32_e32 v100, v0
	v_mov_b32_e32 v101, v0
	v_mov_b32_e32 v102, v0
	v_mov_b32_e32 v103, v0
	v_mov_b32_e32 v112, v0
	v_mov_b32_e32 v113, v0
	v_mov_b32_e32 v114, v0
	v_mov_b32_e32 v115, v0
	v_mov_b32_e32 v116, v0
	v_mov_b32_e32 v117, v0
	v_mov_b32_e32 v118, v0
	v_mov_b32_e32 v119, v0
	v_mov_b32_e32 v72, v0
	v_mov_b32_e32 v73, v0
	v_mov_b32_e32 v74, v0
	v_mov_b32_e32 v75, v0
	v_mov_b32_e32 v76, v0
	v_mov_b32_e32 v77, v0
	v_mov_b32_e32 v78, v0
	v_mov_b32_e32 v79, v0
	v_mov_b32_e32 v88, v0
	v_mov_b32_e32 v89, v0
	v_mov_b32_e32 v90, v0
	v_mov_b32_e32 v91, v0
	v_mov_b32_e32 v92, v0
	v_mov_b32_e32 v93, v0
	v_mov_b32_e32 v94, v0
	v_mov_b32_e32 v95, v0
	v_mov_b32_e32 v104, v0
	v_mov_b32_e32 v105, v0
	v_mov_b32_e32 v106, v0
	v_mov_b32_e32 v107, v0
	v_mov_b32_e32 v108, v0
	v_mov_b32_e32 v109, v0
	v_mov_b32_e32 v110, v0
	v_mov_b32_e32 v111, v0
	v_mov_b32_e32 v120, v0
	v_mov_b32_e32 v121, v0
	v_mov_b32_e32 v122, v0
	v_mov_b32_e32 v123, v0
	v_mov_b32_e32 v124, v0
	v_mov_b32_e32 v125, v0
	v_mov_b32_e32 v126, v0
	v_mov_b32_e32 v127, v0
.LBB0_1094:
	ds_read_b128 v[132:135], v214
	ds_read_b128 v[136:139], v214 offset:1024
	ds_read_b128 v[140:143], v214 offset:2048
	ds_read_b128 v[144:147], v214 offset:3072
	ds_read_b128 v[148:151], v215
	ds_read_b128 v[152:155], v215 offset:1024
	ds_read_b128 v[156:159], v215 offset:2048
	ds_read_b128 v[160:163], v215 offset:3072
	s_add_i32 s56, s55, 2
	s_add_u32 s4, s25, s26
	s_addc_u32 s28, s54, s27
	s_cmpk_eq_i32 s26, 0x1f00
	s_cselect_b32 s29, s1, s28
	s_cselect_b32 s28, s0, s4
	s_cselect_b32 s4, 0, s56
	s_cselect_b32 s58, s53, s24
	v_lshl_add_u64 v[222:223], v[130:131], 0, s[26:27]
	s_add_i32 m0, s37, 0xc000
	ds_read_b128 v[164:167], v216
	ds_read_b128 v[188:191], v216 offset:1024
	ds_read_b128 v[192:195], v216 offset:2048
	ds_read_b128 v[196:199], v216 offset:3072
	ds_read_b128 v[200:203], v216 offset:4096
	ds_read_b128 v[204:207], v216 offset:5120
	ds_read_b128 v[208:211], v216 offset:6144
	ds_read_b128 v[218:221], v216 offset:7168
	global_load_lds_dwordx4 v[222:223], off
	v_lshl_add_u64 v[222:223], v[128:129], 0, s[26:27]
	s_add_i32 m0, s37, 0xe000
	s_nop 0
	global_load_lds_dwordx4 v[222:223], off
	s_waitcnt vmcnt(8)
	s_waitcnt lgkmcnt(0)
	s_barrier
	s_setprio 1
	s_waitcnt lgkmcnt(0)
	v_mfma_f32_16x16x32_bf16 v[124:127], v[132:135], v[164:167], v[124:127]
	v_mfma_f32_16x16x32_bf16 v[120:123], v[140:143], v[164:167], v[120:123]
	v_mfma_f32_16x16x32_bf16 v[108:111], v[132:135], v[192:195], v[108:111]
	v_mfma_f32_16x16x32_bf16 v[104:107], v[140:143], v[192:195], v[104:107]
	v_mfma_f32_16x16x32_bf16 v[92:95], v[132:135], v[200:203], v[92:95]
	v_mfma_f32_16x16x32_bf16 v[88:91], v[140:143], v[200:203], v[88:91]
	v_mfma_f32_16x16x32_bf16 v[76:79], v[132:135], v[208:211], v[76:79]
	v_mfma_f32_16x16x32_bf16 v[72:75], v[140:143], v[208:211], v[72:75]
	v_mfma_f32_16x16x32_bf16 v[124:127], v[136:139], v[188:191], v[124:127]
	v_mfma_f32_16x16x32_bf16 v[120:123], v[144:147], v[188:191], v[120:123]
	v_mfma_f32_16x16x32_bf16 v[108:111], v[136:139], v[196:199], v[108:111]
	v_mfma_f32_16x16x32_bf16 v[104:107], v[144:147], v[196:199], v[104:107]
	v_mfma_f32_16x16x32_bf16 v[92:95], v[136:139], v[204:207], v[92:95]
	v_mfma_f32_16x16x32_bf16 v[88:91], v[144:147], v[204:207], v[88:91]
	v_mfma_f32_16x16x32_bf16 v[76:79], v[136:139], v[218:221], v[76:79]
	v_mfma_f32_16x16x32_bf16 v[72:75], v[144:147], v[218:221], v[72:75]
	s_setprio 0
	s_setprio 1
	v_mfma_f32_16x16x32_bf16 v[116:119], v[148:151], v[164:167], v[116:119]
	v_mfma_f32_16x16x32_bf16 v[112:115], v[156:159], v[164:167], v[112:115]
	v_mfma_f32_16x16x32_bf16 v[100:103], v[148:151], v[192:195], v[100:103]
	v_mfma_f32_16x16x32_bf16 v[96:99], v[156:159], v[192:195], v[96:99]
	v_mfma_f32_16x16x32_bf16 v[84:87], v[148:151], v[200:203], v[84:87]
	v_mfma_f32_16x16x32_bf16 v[80:83], v[156:159], v[200:203], v[80:83]
	v_mfma_f32_16x16x32_bf16 v[68:71], v[148:151], v[208:211], v[68:71]
	v_mfma_f32_16x16x32_bf16 v[64:67], v[156:159], v[208:211], v[64:67]
	v_mfma_f32_16x16x32_bf16 v[116:119], v[152:155], v[188:191], v[116:119]
	v_mfma_f32_16x16x32_bf16 v[112:115], v[160:163], v[188:191], v[112:115]
	v_mfma_f32_16x16x32_bf16 v[100:103], v[152:155], v[196:199], v[100:103]
	v_mfma_f32_16x16x32_bf16 v[96:99], v[160:163], v[196:199], v[96:99]
	v_mfma_f32_16x16x32_bf16 v[84:87], v[152:155], v[204:207], v[84:87]
	v_mfma_f32_16x16x32_bf16 v[80:83], v[160:163], v[204:207], v[80:83]
	v_mfma_f32_16x16x32_bf16 v[68:71], v[152:155], v[218:221], v[68:71]
	v_mfma_f32_16x16x32_bf16 v[64:67], v[160:163], v[218:221], v[64:67]
	s_setprio 0
	s_barrier
	s_add_i32 s57, s48, s36
	v_lshl_add_u64 v[222:223], s[28:29], 0, v[176:177]
	s_mov_b32 m0, s57
	ds_read_b128 v[164:167], v216 offset:16384
	ds_read_b128 v[188:191], v216 offset:17408
	ds_read_b128 v[192:195], v216 offset:18432
	ds_read_b128 v[196:199], v216 offset:19456
	ds_read_b128 v[200:203], v216 offset:20480
	ds_read_b128 v[204:207], v216 offset:21504
	ds_read_b128 v[208:211], v216 offset:22528
	ds_read_b128 v[218:221], v216 offset:23552
	global_load_lds_dwordx4 v[222:223], off
	s_add_i32 m0, s57, 0x2000
	s_add_u32 s60, s28, 0x100000
	v_lshl_add_u64 v[224:225], s[28:29], 0, v[178:179]
	s_addc_u32 s61, s29, 0
	s_add_i32 s57, s49, s36
	global_load_lds_dwordx4 v[224:225], off
	v_lshl_add_u64 v[226:227], s[60:61], 0, v[176:177]
	s_mov_b32 m0, s57
	s_ashr_i32 s59, s58, 31
	global_load_lds_dwordx4 v[226:227], off
	s_add_i32 m0, s57, 0x2000
	s_mul_i32 s58, s58, 0x210000
	s_mov_b32 s59, 0
	s_add_u32 s57, s34, s58
	v_lshl_add_u64 v[226:227], s[60:61], 0, v[178:179]
	s_addc_u32 s60, s35, s59
	s_lshl_b64 s[58:59], s[4:5], 7
	s_add_u32 s58, s57, s58
	s_addc_u32 s59, s60, s59
	global_load_lds_dwordx4 v[226:227], off
	v_lshl_add_u64 v[226:227], s[58:59], 0, v[172:173]
	s_mov_b32 m0, s37
	s_nop 0
	global_load_lds_dwordx4 v[226:227], off
	v_lshl_add_u64 v[226:227], s[58:59], 0, v[174:175]
	s_mov_b32 m0, s38
	s_nop 0
	global_load_lds_dwordx4 v[226:227], off
	s_waitcnt vmcnt(8)
	s_waitcnt lgkmcnt(0)
	s_barrier
	s_setprio 1
	s_waitcnt lgkmcnt(0)
	v_mfma_f32_16x16x32_bf16 v[60:63], v[132:135], v[164:167], v[60:63]
	v_mfma_f32_16x16x32_bf16 v[56:59], v[140:143], v[164:167], v[56:59]
	v_mfma_f32_16x16x32_bf16 v[44:47], v[132:135], v[192:195], v[44:47]
	v_mfma_f32_16x16x32_bf16 v[40:43], v[140:143], v[192:195], v[40:43]
	v_mfma_f32_16x16x32_bf16 v[28:31], v[132:135], v[200:203], v[28:31]
	v_mfma_f32_16x16x32_bf16 v[24:27], v[140:143], v[200:203], v[24:27]
	v_mfma_f32_16x16x32_bf16 v[12:15], v[132:135], v[208:211], v[12:15]
	v_mfma_f32_16x16x32_bf16 v[8:11], v[140:143], v[208:211], v[8:11]
	v_mfma_f32_16x16x32_bf16 v[60:63], v[136:139], v[188:191], v[60:63]
	v_mfma_f32_16x16x32_bf16 v[56:59], v[144:147], v[188:191], v[56:59]
	v_mfma_f32_16x16x32_bf16 v[44:47], v[136:139], v[196:199], v[44:47]
	v_mfma_f32_16x16x32_bf16 v[40:43], v[144:147], v[196:199], v[40:43]
	v_mfma_f32_16x16x32_bf16 v[28:31], v[136:139], v[204:207], v[28:31]
	v_mfma_f32_16x16x32_bf16 v[24:27], v[144:147], v[204:207], v[24:27]
	v_mfma_f32_16x16x32_bf16 v[12:15], v[136:139], v[218:221], v[12:15]
	v_mfma_f32_16x16x32_bf16 v[8:11], v[144:147], v[218:221], v[8:11]
	s_setprio 0
	s_setprio 1
	v_mfma_f32_16x16x32_bf16 v[52:55], v[148:151], v[164:167], v[52:55]
	v_mfma_f32_16x16x32_bf16 v[48:51], v[156:159], v[164:167], v[48:51]
	v_mfma_f32_16x16x32_bf16 v[36:39], v[148:151], v[192:195], v[36:39]
	v_mfma_f32_16x16x32_bf16 v[32:35], v[156:159], v[192:195], v[32:35]
	v_mfma_f32_16x16x32_bf16 v[20:23], v[148:151], v[200:203], v[20:23]
	v_mfma_f32_16x16x32_bf16 v[16:19], v[156:159], v[200:203], v[16:19]
	v_mfma_f32_16x16x32_bf16 v[4:7], v[148:151], v[208:211], v[4:7]
	v_mfma_f32_16x16x32_bf16 v[0:3], v[156:159], v[208:211], v[0:3]
	v_mfma_f32_16x16x32_bf16 v[52:55], v[152:155], v[188:191], v[52:55]
	v_mfma_f32_16x16x32_bf16 v[48:51], v[160:163], v[188:191], v[48:51]
	v_mfma_f32_16x16x32_bf16 v[36:39], v[152:155], v[196:199], v[36:39]
	v_mfma_f32_16x16x32_bf16 v[32:35], v[160:163], v[196:199], v[32:35]
	v_mfma_f32_16x16x32_bf16 v[20:23], v[152:155], v[204:207], v[20:23]
	v_mfma_f32_16x16x32_bf16 v[16:19], v[160:163], v[204:207], v[16:19]
	v_mfma_f32_16x16x32_bf16 v[4:7], v[152:155], v[218:221], v[4:7]
	v_mfma_f32_16x16x32_bf16 v[0:3], v[160:163], v[218:221], v[0:3]
	s_setprio 0
	s_barrier
	s_add_i32 s61, 0, 0x18000
	s_add_i32 s62, 0, 0x1c000
	v_add_u32_e32 v144, s61, v212
	v_add_u32_e32 v160, s62, v212
	ds_read_b128 v[132:135], v144
	ds_read_b128 v[136:139], v144 offset:1024
	ds_read_b128 v[140:143], v144 offset:2048
	ds_read_b128 v[144:147], v144 offset:3072
	ds_read_b128 v[148:151], v160
	ds_read_b128 v[152:155], v160 offset:1024
	ds_read_b128 v[156:159], v160 offset:2048
	ds_read_b128 v[160:163], v160 offset:3072
	s_add_u32 s58, s58, 0x108000
	s_addc_u32 s59, s59, 0
	s_mov_b32 m0, s39
	v_lshl_add_u64 v[226:227], s[58:59], 0, v[172:173]
	ds_read_b128 v[164:167], v216 offset:32768
	ds_read_b128 v[188:191], v216 offset:33792
	ds_read_b128 v[192:195], v216 offset:34816
	ds_read_b128 v[196:199], v216 offset:35840
	ds_read_b128 v[200:203], v216 offset:36864
	ds_read_b128 v[204:207], v216 offset:37888
	ds_read_b128 v[208:211], v216 offset:38912
	ds_read_b128 v[218:221], v216 offset:39936
	global_load_lds_dwordx4 v[226:227], off
	v_lshl_add_u64 v[226:227], s[58:59], 0, v[174:175]
	s_mov_b32 m0, s40
	s_nop 0
	global_load_lds_dwordx4 v[226:227], off
	s_waitcnt vmcnt(8)
	s_waitcnt lgkmcnt(0)
	s_barrier
	s_setprio 1
	s_waitcnt lgkmcnt(0)
	v_mfma_f32_16x16x32_bf16 v[124:127], v[132:135], v[164:167], v[124:127]
	v_mfma_f32_16x16x32_bf16 v[120:123], v[140:143], v[164:167], v[120:123]
	v_mfma_f32_16x16x32_bf16 v[108:111], v[132:135], v[192:195], v[108:111]
	v_mfma_f32_16x16x32_bf16 v[104:107], v[140:143], v[192:195], v[104:107]
	v_mfma_f32_16x16x32_bf16 v[92:95], v[132:135], v[200:203], v[92:95]
	v_mfma_f32_16x16x32_bf16 v[88:91], v[140:143], v[200:203], v[88:91]
	v_mfma_f32_16x16x32_bf16 v[76:79], v[132:135], v[208:211], v[76:79]
	v_mfma_f32_16x16x32_bf16 v[72:75], v[140:143], v[208:211], v[72:75]
	v_mfma_f32_16x16x32_bf16 v[124:127], v[136:139], v[188:191], v[124:127]
	v_mfma_f32_16x16x32_bf16 v[120:123], v[144:147], v[188:191], v[120:123]
	v_mfma_f32_16x16x32_bf16 v[108:111], v[136:139], v[196:199], v[108:111]
	v_mfma_f32_16x16x32_bf16 v[104:107], v[144:147], v[196:199], v[104:107]
	v_mfma_f32_16x16x32_bf16 v[92:95], v[136:139], v[204:207], v[92:95]
	v_mfma_f32_16x16x32_bf16 v[88:91], v[144:147], v[204:207], v[88:91]
	v_mfma_f32_16x16x32_bf16 v[76:79], v[136:139], v[218:221], v[76:79]
	v_mfma_f32_16x16x32_bf16 v[72:75], v[144:147], v[218:221], v[72:75]
	s_setprio 0
	s_setprio 1
	v_mfma_f32_16x16x32_bf16 v[116:119], v[148:151], v[164:167], v[116:119]
	v_mfma_f32_16x16x32_bf16 v[112:115], v[156:159], v[164:167], v[112:115]
	v_mfma_f32_16x16x32_bf16 v[100:103], v[148:151], v[192:195], v[100:103]
	v_mfma_f32_16x16x32_bf16 v[96:99], v[156:159], v[192:195], v[96:99]
	v_mfma_f32_16x16x32_bf16 v[84:87], v[148:151], v[200:203], v[84:87]
	v_mfma_f32_16x16x32_bf16 v[80:83], v[156:159], v[200:203], v[80:83]
	v_mfma_f32_16x16x32_bf16 v[68:71], v[148:151], v[208:211], v[68:71]
	v_mfma_f32_16x16x32_bf16 v[64:67], v[156:159], v[208:211], v[64:67]
	v_mfma_f32_16x16x32_bf16 v[116:119], v[152:155], v[188:191], v[116:119]
	v_mfma_f32_16x16x32_bf16 v[112:115], v[160:163], v[188:191], v[112:115]
	v_mfma_f32_16x16x32_bf16 v[100:103], v[152:155], v[196:199], v[100:103]
	v_mfma_f32_16x16x32_bf16 v[96:99], v[160:163], v[196:199], v[96:99]
	v_mfma_f32_16x16x32_bf16 v[84:87], v[152:155], v[204:207], v[84:87]
	v_mfma_f32_16x16x32_bf16 v[80:83], v[160:163], v[204:207], v[80:83]
	v_mfma_f32_16x16x32_bf16 v[68:71], v[152:155], v[218:221], v[68:71]
	v_mfma_f32_16x16x32_bf16 v[64:67], v[160:163], v[218:221], v[64:67]
	s_setprio 0
	s_barrier
	s_add_i32 s58, s61, s36
	v_lshl_add_u64 v[222:223], v[222:223], 0, s[18:19]
	s_mov_b32 m0, s58
	ds_read_b128 v[164:167], v216 offset:49152
	ds_read_b128 v[188:191], v216 offset:50176
	ds_read_b128 v[192:195], v216 offset:51200
	ds_read_b128 v[196:199], v216 offset:52224
	ds_read_b128 v[200:203], v216 offset:53248
	ds_read_b128 v[204:207], v216 offset:54272
	ds_read_b128 v[208:211], v216 offset:55296
	ds_read_b128 v[218:221], v216 offset:56320
	global_load_lds_dwordx4 v[222:223], off
	s_add_i32 m0, s58, 0x2000
	s_add_u32 s28, s28, 0x100080
	v_lshl_add_u64 v[222:223], v[224:225], 0, s[18:19]
	s_addc_u32 s29, s29, 0
	s_add_i32 s58, s62, s36
	global_load_lds_dwordx4 v[222:223], off
	v_lshl_add_u64 v[222:223], s[28:29], 0, v[176:177]
	s_mov_b32 m0, s58
	s_or_b32 s4, s4, 1
	global_load_lds_dwordx4 v[222:223], off
	v_lshl_add_u64 v[222:223], s[28:29], 0, v[178:179]
	s_add_i32 m0, s58, 0x2000
	s_lshl_b64 s[28:29], s[4:5], 7
	s_add_u32 s28, s57, s28
	s_addc_u32 s29, s60, s29
	global_load_lds_dwordx4 v[222:223], off
	v_lshl_add_u64 v[222:223], s[28:29], 0, v[172:173]
	s_mov_b32 m0, s42
	s_nop 0
	global_load_lds_dwordx4 v[222:223], off
	v_lshl_add_u64 v[222:223], s[28:29], 0, v[174:175]
	s_mov_b32 m0, s43
	s_nop 0
	global_load_lds_dwordx4 v[222:223], off
	s_waitcnt vmcnt(8)
	s_waitcnt lgkmcnt(0)
	s_barrier
	s_setprio 1
	s_waitcnt lgkmcnt(0)
	v_mfma_f32_16x16x32_bf16 v[60:63], v[132:135], v[164:167], v[60:63]
	v_mfma_f32_16x16x32_bf16 v[56:59], v[140:143], v[164:167], v[56:59]
	v_mfma_f32_16x16x32_bf16 v[44:47], v[132:135], v[192:195], v[44:47]
	v_mfma_f32_16x16x32_bf16 v[40:43], v[140:143], v[192:195], v[40:43]
	v_mfma_f32_16x16x32_bf16 v[28:31], v[132:135], v[200:203], v[28:31]
	v_mfma_f32_16x16x32_bf16 v[24:27], v[140:143], v[200:203], v[24:27]
	v_mfma_f32_16x16x32_bf16 v[12:15], v[132:135], v[208:211], v[12:15]
	v_mfma_f32_16x16x32_bf16 v[8:11], v[140:143], v[208:211], v[8:11]
	v_mfma_f32_16x16x32_bf16 v[60:63], v[136:139], v[188:191], v[60:63]
	v_mfma_f32_16x16x32_bf16 v[56:59], v[144:147], v[188:191], v[56:59]
	v_mfma_f32_16x16x32_bf16 v[44:47], v[136:139], v[196:199], v[44:47]
	v_mfma_f32_16x16x32_bf16 v[40:43], v[144:147], v[196:199], v[40:43]
	v_mfma_f32_16x16x32_bf16 v[28:31], v[136:139], v[204:207], v[28:31]
	v_mfma_f32_16x16x32_bf16 v[24:27], v[144:147], v[204:207], v[24:27]
	v_mfma_f32_16x16x32_bf16 v[12:15], v[136:139], v[218:221], v[12:15]
	v_mfma_f32_16x16x32_bf16 v[8:11], v[144:147], v[218:221], v[8:11]
	s_setprio 0
	s_setprio 1
	v_mfma_f32_16x16x32_bf16 v[52:55], v[148:151], v[164:167], v[52:55]
	v_mfma_f32_16x16x32_bf16 v[48:51], v[156:159], v[164:167], v[48:51]
	v_mfma_f32_16x16x32_bf16 v[36:39], v[148:151], v[192:195], v[36:39]
	v_mfma_f32_16x16x32_bf16 v[32:35], v[156:159], v[192:195], v[32:35]
	v_mfma_f32_16x16x32_bf16 v[20:23], v[148:151], v[200:203], v[20:23]
	v_mfma_f32_16x16x32_bf16 v[16:19], v[156:159], v[200:203], v[16:19]
	v_mfma_f32_16x16x32_bf16 v[4:7], v[148:151], v[208:211], v[4:7]
	v_mfma_f32_16x16x32_bf16 v[0:3], v[156:159], v[208:211], v[0:3]
	v_mfma_f32_16x16x32_bf16 v[52:55], v[152:155], v[188:191], v[52:55]
	v_mfma_f32_16x16x32_bf16 v[48:51], v[160:163], v[188:191], v[48:51]
	v_mfma_f32_16x16x32_bf16 v[36:39], v[152:155], v[196:199], v[36:39]
	v_mfma_f32_16x16x32_bf16 v[32:35], v[160:163], v[196:199], v[32:35]
	v_mfma_f32_16x16x32_bf16 v[20:23], v[152:155], v[204:207], v[20:23]
	v_mfma_f32_16x16x32_bf16 v[16:19], v[160:163], v[204:207], v[16:19]
	v_mfma_f32_16x16x32_bf16 v[4:7], v[152:155], v[218:221], v[4:7]
	v_mfma_f32_16x16x32_bf16 v[0:3], v[160:163], v[218:221], v[0:3]
	s_setprio 0
	s_barrier
	s_add_u32 s26, s26, 0x100
	s_addc_u32 s27, s27, 0
	s_cmp_gt_u32 s55, 61
	s_mov_b32 s55, s56
	s_cbranch_scc0 .LBB0_1094
	s_and_b64 vcc, exec, s[20:21]
	s_cbranch_vccz .LBB0_1097
	s_barrier

.LBB0_2780:
	s_sext_i32_i8 s75, s8
	s_add_u32 s8, s18, 0xc400000
	s_mov_b64 s[10:11], 0x80
	s_addc_u32 s9, s19, 0
	s_and_b32 s1, s1, 3
	s_add_i32 m0, s58, 0x18000
	v_lshl_add_u64 v[6:7], v[6:7], 0, s[10:11]
	s_lshl_b32 s13, s0, 13
	s_lshl_b32 s14, s1, 12
	s_waitcnt vmcnt(2)
	s_barrier
	global_load_lds_dwordx4 v[6:7], off
	v_lshl_add_u64 v[4:5], v[4:5], 0, s[10:11]
	s_add_i32 m0, s58, 0x1a000
	s_add_i32 s63, s58, 0x8000
	s_add_i32 s64, s58, 0xa000
	global_load_lds_dwordx4 v[4:5], off
	v_lshl_add_u64 v[0:1], v[0:1], 0, s[10:11]
	s_mov_b32 m0, s63
	s_add_u32 s6, s6, 0x40080
	global_load_lds_dwordx4 v[0:1], off
	v_lshl_add_u64 v[0:1], v[2:3], 0, s[10:11]
	s_mov_b32 m0, s64
	s_addc_u32 s7, s7, 0
	global_load_lds_dwordx4 v[0:1], off
	s_add_i32 m0, s58, 0x1c000
	v_lshl_add_u64 v[0:1], s[6:7], 0, v[132:133]
	global_load_lds_dwordx4 v[0:1], off
	v_lshl_add_u64 v[0:1], s[6:7], 0, v[134:135]
	s_add_i32 m0, s58, 0x1e000
	s_waitcnt vmcnt(0)
	v_lshrrev_b32_e32 v12, 4, v170
	global_load_lds_dwordx4 v[0:1], off
	v_and_b32_e32 v13, 15, v170
	v_and_b32_e32 v12, 3, v12
	v_lshlrev_b32_e32 v1, 4, v12
	v_lshlrev_b32_e32 v3, 2, v13
	v_lshl_or_b32 v2, v13, 6, v1
	v_and_b32_e32 v4, 32, v3
	v_bitop3_b32 v2, v2, s13, v4 bitop3:0xde
	v_lshlrev_b32_e32 v4, 6, v170
	s_movk_i32 s6, 0x3c0
	v_and_or_b32 v1, v4, s6, v1
	v_lshlrev_b32_e32 v4, 2, v170
	s_cmpk_lt_u32 s12, 0x100
	v_and_b32_e32 v4, 32, v4
	s_cselect_b64 s[12:13], -1, 0
	s_cmp_eq_u32 s1, 0
	v_lshl_or_b32 v150, s0, 6, v13
	v_bitop3_b32 v151, s14, v1, v4 bitop3:0xf6
	s_cselect_b64 s[14:15], -1, 0
	s_lshl_b32 s0, s0, 8
	v_lshlrev_b32_e32 v0, 3, v12
	s_add_i32 s0, s0, 0
	s_add_i32 s0, s0, 0x20000
	v_lshl_or_b32 v153, s1, 5, v0
	v_lshlrev_b32_e32 v0, 4, v11
	v_add_u32_e32 v152, s0, v3
	v_and_b32_e32 v0, 0x78000, v0
	v_lshlrev_b32_e32 v3, 11, v10
	v_or3_b32 v0, v8, v0, v3
	v_add_u32_e32 v0, v0, v9
	v_mov_b32_e32 v1, v133
	s_mov_b64 s[6:7], 0x40080
	v_lshl_add_u64 v[0:1], s[16:17], 0, v[0:1]
	v_lshl_add_u64 v[138:139], v[0:1], 0, s[6:7]
	v_lshlrev_b32_e32 v0, 8, v170
	v_cmp_gt_u32_e32 vcc, 2, v12
	v_and_b32_e32 v0, 0x38000, v0
	s_and_b64 s[14:15], s[14:15], vcc
	v_or3_b32 v0, v8, v0, v3
	s_waitcnt vmcnt(6)
	v_add_u32_e32 v0, v0, v9
	v_mov_b32_e32 v1, v133
	s_add_u32 s65, s18, 0x2300100
	v_lshl_add_u64 v[0:1], s[16:17], 0, v[0:1]
	s_addc_u32 s66, s19, 0
	s_add_i32 s67, 0, 0x10000
	s_add_i32 s68, 0, 0x14000
	v_lshlrev_b32_e32 v136, 5, v12
	v_mov_b32_e32 v137, v133
	v_lshl_add_u64 v[140:141], v[0:1], 0, s[6:7]
	v_mov_b64_e32 v[142:143], 0x800
	v_mov_b64_e32 v[144:145], 0x7ff
	s_mov_b64 s[18:19], 0x100
	v_add_u32_e32 v154, s67, v151
	v_add_u32_e32 v155, s68, v151
	v_add_u32_e32 v156, 0, v2
	s_mov_b64 s[20:21], 0x108000
	s_mov_b64 s[22:23], 0x108100
	s_mov_b64 s[24:25], 0x129000
	s_mov_b64 s[26:27], 0x129100
	s_mov_b64 s[28:29], 0x14a000
	s_mov_b64 s[30:31], 0x14a100
	s_mov_b64 s[34:35], 0x16b000
	s_mov_b64 s[36:37], 0x16b100
	s_mov_b64 s[38:39], 0x2000
	s_mov_b64 s[40:41], 0x2400
	s_mov_b64 s[42:43], 0x2800
	s_mov_b64 s[44:45], 0x2c00
	s_barrier
	s_branch .LBB0_2783

.LBB0_2793:
	s_cmp_eq_u32 s75, -1
	v_lshl_add_u32 v146, s48, 8, v150
	s_cbranch_scc1 .LBB0_2796
	v_lshl_add_u32 v157, s74, 10, v152
	ds_read_b32 v162, v157
	v_lshl_or_b32 v148, s75, 8, v153
	v_ashrrev_i32_e32 v147, 31, v146
	v_ashrrev_i32_e32 v149, 31, v148
	v_mul_u32_u24_e32 v158, 0x2100, v146
	v_mov_b32_e32 v159, 0
	v_lshl_add_u64 v[158:159], s[8:9], 0, v[158:159]
	v_lshlrev_b64 v[164:165], 1, v[148:149]
	s_waitcnt lgkmcnt(0)
	v_pk_mul_f32 v[172:173], v[64:65], v[162:163] op_sel_hi:[1,0]
	v_lshl_add_u64 v[148:149], v[158:159], 0, v[164:165]
	v_pk_mul_f32 v[158:159], v[70:71], v[162:163] op_sel_hi:[1,0]
	v_pk_mul_f32 v[160:161], v[68:69], v[162:163] op_sel_hi:[1,0]
	v_pk_mul_f32 v[166:167], v[66:67], v[162:163] op_sel_hi:[1,0]
	v_max_f32_e32 v163, 0, v173
	v_mul_f32_e32 v163, v163, v163
	v_max_f32_e32 v147, 0, v160
	v_max_f32_e32 v161, 0, v161
	v_max_f32_e32 v158, 0, v158
	v_pk_mul_f32 v[122:123], v[122:123], v[162:163] op_sel_hi:[1,0]
	v_pk_mul_f32 v[120:121], v[120:121], v[162:163] op_sel_hi:[1,0]
	v_max_f32_e32 v160, 0, v172
	v_mul_f32_e32 v147, v147, v147
	v_mul_f32_e32 v161, v161, v161
	v_max_f32_e32 v166, 0, v166
	v_mul_f32_e32 v169, v158, v158
	v_max_f32_e32 v158, 0, v159
	v_max_f32_e32 v159, 0, v167
	v_pk_mul_f32 v[126:127], v[126:127], v[162:163] op_sel_hi:[1,0]
	v_pk_mul_f32 v[124:125], v[124:125], v[162:163] op_sel_hi:[1,0]
	v_max_f32_e32 v120, 0, v120
	v_max_f32_e32 v121, 0, v121
	v_max_f32_e32 v122, 0, v122
	v_mul_f32_e32 v160, v160, v160
	v_mul_f32_e32 v166, v166, v166
	v_mul_f32_e32 v167, v158, v158
	v_mul_f32_e32 v171, v159, v159
	v_cvt_pk_bf16_f32 v158, v147, v161
	v_max_f32_e32 v124, 0, v124
	v_mul_f32_e32 v147, v120, v120
	v_max_f32_e32 v120, 0, v125
	v_mul_f32_e32 v125, v121, v121
	v_max_f32_e32 v121, 0, v126
	v_mul_f32_e32 v126, v122, v122
	v_max_f32_e32 v122, 0, v127
	v_max_f32_e32 v123, 0, v123
	v_cvt_pk_bf16_f32 v159, v169, v167
	v_cvt_pk_bf16_f32 v160, v160, v163
	v_cvt_pk_bf16_f32 v161, v166, v171
	global_store_dwordx4 v[148:149], v[158:161], off sc1 nt
	s_nop 1
	v_mul_f32_e32 v124, v124, v124
	v_mul_f32_e32 v120, v120, v120
	v_mul_f32_e32 v121, v121, v121
	v_mul_f32_e32 v122, v122, v122
	v_mul_f32_e32 v123, v123, v123
	v_cvt_pk_bf16_f32 v120, v124, v120
	v_cvt_pk_bf16_f32 v121, v121, v122
	v_cvt_pk_bf16_f32 v122, v147, v125
	v_cvt_pk_bf16_f32 v123, v126, v123
	v_lshl_add_u64 v[124:125], v[148:149], 0, s[18:19]
	global_store_dwordx4 v[124:125], v[120:123], off sc1 nt
	s_nop 1
	ds_read_b32 v124, v157 offset:64
	v_or_b32_e32 v120, 16, v146
	v_ashrrev_i32_e32 v121, 31, v120
	v_mul_u32_u24_e32 v120, 0x2100, v120
	v_mov_b32_e32 v121, 0
	v_lshl_add_u64 v[120:121], s[8:9], 0, v[120:121]
	s_waitcnt lgkmcnt(0)
	v_pk_mul_f32 v[160:161], v[56:57], v[124:125] op_sel_hi:[1,0]
	v_lshl_add_u64 v[126:127], v[120:121], 0, v[164:165]
	v_pk_mul_f32 v[120:121], v[62:63], v[124:125] op_sel_hi:[1,0]
	v_pk_mul_f32 v[122:123], v[60:61], v[124:125] op_sel_hi:[1,0]
	v_pk_mul_f32 v[158:159], v[58:59], v[124:125] op_sel_hi:[1,0]
	v_max_f32_e32 v125, 0, v160
	v_max_f32_e32 v122, 0, v122
	v_mul_f32_e32 v125, v125, v125
	v_max_f32_e32 v123, 0, v123
	v_max_f32_e32 v120, 0, v120
	v_mul_f32_e32 v122, v122, v122
	v_max_f32_e32 v147, 0, v161
	v_mul_f32_e32 v123, v123, v123
	v_max_f32_e32 v158, 0, v158
	v_mul_f32_e32 v160, v120, v120
	v_max_f32_e32 v120, 0, v121
	v_max_f32_e32 v121, 0, v159
	v_pk_mul_f32 v[114:115], v[114:115], v[124:125] op_sel_hi:[1,0]
	v_pk_mul_f32 v[112:113], v[112:113], v[124:125] op_sel_hi:[1,0]
	v_mul_f32_e32 v147, v147, v147
	v_mul_f32_e32 v158, v158, v158
	v_mul_f32_e32 v159, v120, v120
	v_mul_f32_e32 v161, v121, v121
	v_cvt_pk_bf16_f32 v120, v122, v123
	v_pk_mul_f32 v[118:119], v[118:119], v[124:125] op_sel_hi:[1,0]
	v_pk_mul_f32 v[116:117], v[116:117], v[124:125] op_sel_hi:[1,0]
	v_max_f32_e32 v112, 0, v112
	v_max_f32_e32 v113, 0, v113
	v_max_f32_e32 v114, 0, v114
	v_cvt_pk_bf16_f32 v121, v160, v159
	v_cvt_pk_bf16_f32 v122, v125, v147
	v_cvt_pk_bf16_f32 v123, v158, v161
	global_store_dwordx4 v[126:127], v[120:123], off sc1 nt
	s_nop 1
	v_max_f32_e32 v116, 0, v116
	v_mul_f32_e32 v120, v112, v112
	v_max_f32_e32 v112, 0, v117
	v_mul_f32_e32 v117, v113, v113
	v_max_f32_e32 v113, 0, v118
	v_mul_f32_e32 v118, v114, v114
	v_max_f32_e32 v114, 0, v119
	v_max_f32_e32 v115, 0, v115
	v_mul_f32_e32 v116, v116, v116
	v_mul_f32_e32 v112, v112, v112
	v_mul_f32_e32 v113, v113, v113
	v_mul_f32_e32 v114, v114, v114
	v_mul_f32_e32 v115, v115, v115
	v_cvt_pk_bf16_f32 v112, v116, v112
	v_cvt_pk_bf16_f32 v113, v113, v114
	v_cvt_pk_bf16_f32 v114, v120, v117
	v_cvt_pk_bf16_f32 v115, v118, v115
	v_lshl_add_u64 v[116:117], v[126:127], 0, s[18:19]
	global_store_dwordx4 v[116:117], v[112:115], off sc1 nt
	s_nop 1
	ds_read_b32 v116, v157 offset:128
	v_or_b32_e32 v112, 32, v146
	v_ashrrev_i32_e32 v113, 31, v112
	v_mul_u32_u24_e32 v112, 0x2100, v112
	v_mov_b32_e32 v113, 0
	v_lshl_add_u64 v[112:113], s[8:9], 0, v[112:113]
	s_waitcnt lgkmcnt(0)
	v_pk_mul_f32 v[122:123], v[40:41], v[116:117] op_sel_hi:[1,0]
	v_lshl_add_u64 v[118:119], v[112:113], 0, v[164:165]
	v_pk_mul_f32 v[112:113], v[50:51], v[116:117] op_sel_hi:[1,0]
	v_pk_mul_f32 v[114:115], v[48:49], v[116:117] op_sel_hi:[1,0]
	v_pk_mul_f32 v[120:121], v[42:43], v[116:117] op_sel_hi:[1,0]
	v_max_f32_e32 v117, 0, v122
	v_max_f32_e32 v114, 0, v114
	v_mul_f32_e32 v117, v117, v117
	v_max_f32_e32 v115, 0, v115
	v_max_f32_e32 v112, 0, v112
	v_mul_f32_e32 v114, v114, v114
	v_max_f32_e32 v122, 0, v123
	v_mul_f32_e32 v115, v115, v115
	v_max_f32_e32 v120, 0, v120
	v_mul_f32_e32 v123, v112, v112
	v_max_f32_e32 v112, 0, v113
	v_max_f32_e32 v113, 0, v121
	v_pk_mul_f32 v[106:107], v[106:107], v[116:117] op_sel_hi:[1,0]
	v_pk_mul_f32 v[104:105], v[104:105], v[116:117] op_sel_hi:[1,0]
	v_mul_f32_e32 v122, v122, v122
	v_mul_f32_e32 v120, v120, v120
	v_mul_f32_e32 v121, v112, v112
	v_mul_f32_e32 v124, v113, v113
	v_cvt_pk_bf16_f32 v112, v114, v115
	v_pk_mul_f32 v[110:111], v[110:111], v[116:117] op_sel_hi:[1,0]
	v_pk_mul_f32 v[108:109], v[108:109], v[116:117] op_sel_hi:[1,0]
	v_max_f32_e32 v104, 0, v104
	v_max_f32_e32 v105, 0, v105
	v_max_f32_e32 v106, 0, v106
	v_cvt_pk_bf16_f32 v113, v123, v121
	v_cvt_pk_bf16_f32 v114, v117, v122
	v_cvt_pk_bf16_f32 v115, v120, v124
	global_store_dwordx4 v[118:119], v[112:115], off sc1 nt
	s_nop 1
	v_max_f32_e32 v108, 0, v108
	v_mul_f32_e32 v112, v104, v104
	v_max_f32_e32 v104, 0, v109
	v_mul_f32_e32 v109, v105, v105
	v_max_f32_e32 v105, 0, v110
	v_mul_f32_e32 v110, v106, v106
	v_max_f32_e32 v106, 0, v111
	v_max_f32_e32 v107, 0, v107
	v_mul_f32_e32 v108, v108, v108
	v_mul_f32_e32 v104, v104, v104
	v_mul_f32_e32 v105, v105, v105
	v_mul_f32_e32 v106, v106, v106
	v_mul_f32_e32 v107, v107, v107
	v_cvt_pk_bf16_f32 v104, v108, v104
	v_cvt_pk_bf16_f32 v105, v105, v106
	v_cvt_pk_bf16_f32 v106, v112, v109
	v_cvt_pk_bf16_f32 v107, v110, v107
	v_lshl_add_u64 v[108:109], v[118:119], 0, s[18:19]
	global_store_dwordx4 v[108:109], v[104:107], off sc1 nt
	s_nop 1
	ds_read_b32 v108, v157 offset:192
	v_or_b32_e32 v104, 48, v146
	v_ashrrev_i32_e32 v105, 31, v104
	v_mul_u32_u24_e32 v104, 0x2100, v104
	v_mov_b32_e32 v105, 0
	v_lshl_add_u64 v[104:105], s[8:9], 0, v[104:105]
	s_waitcnt lgkmcnt(0)
	v_pk_mul_f32 v[114:115], v[32:33], v[108:109] op_sel_hi:[1,0]
	v_lshl_add_u64 v[110:111], v[104:105], 0, v[164:165]
	v_pk_mul_f32 v[104:105], v[38:39], v[108:109] op_sel_hi:[1,0]
	v_pk_mul_f32 v[106:107], v[36:37], v[108:109] op_sel_hi:[1,0]
	v_pk_mul_f32 v[112:113], v[34:35], v[108:109] op_sel_hi:[1,0]
	v_max_f32_e32 v109, 0, v114
	v_max_f32_e32 v106, 0, v106
	v_mul_f32_e32 v109, v109, v109
	v_max_f32_e32 v107, 0, v107
	v_max_f32_e32 v104, 0, v104
	v_mul_f32_e32 v106, v106, v106
	v_max_f32_e32 v114, 0, v115
	v_mul_f32_e32 v107, v107, v107
	v_max_f32_e32 v112, 0, v112
	v_mul_f32_e32 v115, v104, v104
	v_max_f32_e32 v104, 0, v105
	v_max_f32_e32 v105, 0, v113
	v_pk_mul_f32 v[98:99], v[98:99], v[108:109] op_sel_hi:[1,0]
	v_pk_mul_f32 v[96:97], v[96:97], v[108:109] op_sel_hi:[1,0]
	v_mul_f32_e32 v114, v114, v114
	v_mul_f32_e32 v112, v112, v112
	v_mul_f32_e32 v113, v104, v104
	v_mul_f32_e32 v116, v105, v105
	v_cvt_pk_bf16_f32 v104, v106, v107
	v_pk_mul_f32 v[102:103], v[102:103], v[108:109] op_sel_hi:[1,0]
	v_pk_mul_f32 v[100:101], v[100:101], v[108:109] op_sel_hi:[1,0]
	v_max_f32_e32 v96, 0, v96
	v_max_f32_e32 v97, 0, v97
	v_max_f32_e32 v98, 0, v98
	v_cvt_pk_bf16_f32 v105, v115, v113
	v_cvt_pk_bf16_f32 v106, v109, v114
	v_cvt_pk_bf16_f32 v107, v112, v116
	global_store_dwordx4 v[110:111], v[104:107], off sc1 nt
	s_nop 1
	v_max_f32_e32 v100, 0, v100
	v_mul_f32_e32 v104, v96, v96
	v_max_f32_e32 v96, 0, v101
	v_mul_f32_e32 v101, v97, v97
	v_max_f32_e32 v97, 0, v102
	v_mul_f32_e32 v102, v98, v98
	v_max_f32_e32 v98, 0, v103
	v_max_f32_e32 v99, 0, v99
	v_mul_f32_e32 v100, v100, v100
	v_mul_f32_e32 v96, v96, v96
	v_mul_f32_e32 v97, v97, v97
	v_mul_f32_e32 v98, v98, v98
	v_mul_f32_e32 v99, v99, v99
	v_cvt_pk_bf16_f32 v96, v100, v96
	v_cvt_pk_bf16_f32 v97, v97, v98
	v_cvt_pk_bf16_f32 v98, v104, v101
	v_cvt_pk_bf16_f32 v99, v102, v99
	v_lshl_add_u64 v[100:101], v[110:111], 0, s[18:19]
	global_store_dwordx4 v[100:101], v[96:99], off sc1 nt
	s_nop 1
	ds_read_b32 v100, v157 offset:512
	v_lshl_add_u64 v[102:103], v[148:149], 0, s[20:21]
	s_waitcnt lgkmcnt(0)
	v_pk_mul_f32 v[106:107], v[24:25], v[100:101] op_sel_hi:[1,0]
	v_pk_mul_f32 v[96:97], v[30:31], v[100:101] op_sel_hi:[1,0]
	v_pk_mul_f32 v[98:99], v[28:29], v[100:101] op_sel_hi:[1,0]
	v_pk_mul_f32 v[104:105], v[26:27], v[100:101] op_sel_hi:[1,0]
	v_max_f32_e32 v101, 0, v106
	v_max_f32_e32 v98, 0, v98
	v_mul_f32_e32 v101, v101, v101
	v_max_f32_e32 v99, 0, v99
	v_max_f32_e32 v96, 0, v96
	v_mul_f32_e32 v98, v98, v98
	v_max_f32_e32 v106, 0, v107
	v_mul_f32_e32 v99, v99, v99
	v_max_f32_e32 v104, 0, v104
	v_mul_f32_e32 v107, v96, v96
	v_max_f32_e32 v96, 0, v97
	v_max_f32_e32 v97, 0, v105
	v_pk_mul_f32 v[90:91], v[90:91], v[100:101] op_sel_hi:[1,0]
	v_pk_mul_f32 v[88:89], v[88:89], v[100:101] op_sel_hi:[1,0]
	v_mul_f32_e32 v106, v106, v106
	v_mul_f32_e32 v104, v104, v104
	v_mul_f32_e32 v105, v96, v96
	v_mul_f32_e32 v108, v97, v97
	v_cvt_pk_bf16_f32 v96, v98, v99
	v_pk_mul_f32 v[94:95], v[94:95], v[100:101] op_sel_hi:[1,0]
	v_pk_mul_f32 v[92:93], v[92:93], v[100:101] op_sel_hi:[1,0]
	v_max_f32_e32 v88, 0, v88
	v_max_f32_e32 v89, 0, v89
	v_max_f32_e32 v90, 0, v90
	v_cvt_pk_bf16_f32 v97, v107, v105
	v_cvt_pk_bf16_f32 v98, v101, v106
	v_cvt_pk_bf16_f32 v99, v104, v108
	global_store_dwordx4 v[102:103], v[96:99], off sc1 nt
	s_nop 1
	v_max_f32_e32 v92, 0, v92
	v_mul_f32_e32 v96, v88, v88
	v_max_f32_e32 v88, 0, v93
	v_mul_f32_e32 v93, v89, v89
	v_max_f32_e32 v89, 0, v94
	v_mul_f32_e32 v94, v90, v90
	v_max_f32_e32 v90, 0, v95
	v_max_f32_e32 v91, 0, v91
	v_mul_f32_e32 v92, v92, v92
	v_mul_f32_e32 v88, v88, v88
	v_mul_f32_e32 v89, v89, v89
	v_mul_f32_e32 v90, v90, v90
	v_mul_f32_e32 v91, v91, v91
	v_cvt_pk_bf16_f32 v88, v92, v88
	v_cvt_pk_bf16_f32 v89, v89, v90
	v_cvt_pk_bf16_f32 v90, v96, v93
	v_cvt_pk_bf16_f32 v91, v94, v91
	v_lshl_add_u64 v[92:93], v[148:149], 0, s[22:23]
	global_store_dwordx4 v[92:93], v[88:91], off sc1 nt
	s_nop 1
	ds_read_b32 v92, v157 offset:576
	v_lshl_add_u64 v[94:95], v[148:149], 0, s[24:25]
	s_waitcnt lgkmcnt(0)
	v_pk_mul_f32 v[98:99], v[16:17], v[92:93] op_sel_hi:[1,0]
	v_pk_mul_f32 v[88:89], v[22:23], v[92:93] op_sel_hi:[1,0]
	v_pk_mul_f32 v[90:91], v[20:21], v[92:93] op_sel_hi:[1,0]
	v_pk_mul_f32 v[96:97], v[18:19], v[92:93] op_sel_hi:[1,0]
	v_max_f32_e32 v93, 0, v98
	v_max_f32_e32 v90, 0, v90
	v_mul_f32_e32 v93, v93, v93
	v_max_f32_e32 v91, 0, v91
	v_max_f32_e32 v88, 0, v88
	v_mul_f32_e32 v90, v90, v90
	v_max_f32_e32 v98, 0, v99
	v_mul_f32_e32 v91, v91, v91
	v_max_f32_e32 v96, 0, v96
	v_mul_f32_e32 v99, v88, v88
	v_max_f32_e32 v88, 0, v89
	v_max_f32_e32 v89, 0, v97
	v_pk_mul_f32 v[82:83], v[82:83], v[92:93] op_sel_hi:[1,0]
	v_pk_mul_f32 v[80:81], v[80:81], v[92:93] op_sel_hi:[1,0]
	v_mul_f32_e32 v98, v98, v98
	v_mul_f32_e32 v96, v96, v96
	v_mul_f32_e32 v97, v88, v88
	v_mul_f32_e32 v100, v89, v89
	v_cvt_pk_bf16_f32 v88, v90, v91
	v_pk_mul_f32 v[86:87], v[86:87], v[92:93] op_sel_hi:[1,0]
	v_pk_mul_f32 v[84:85], v[84:85], v[92:93] op_sel_hi:[1,0]
	v_max_f32_e32 v80, 0, v80
	v_max_f32_e32 v81, 0, v81
	v_max_f32_e32 v82, 0, v82
	v_cvt_pk_bf16_f32 v89, v99, v97
	v_cvt_pk_bf16_f32 v90, v93, v98
	v_cvt_pk_bf16_f32 v91, v96, v100
	global_store_dwordx4 v[94:95], v[88:91], off sc1 nt
	s_nop 1
	v_max_f32_e32 v84, 0, v84
	v_mul_f32_e32 v88, v80, v80
	v_max_f32_e32 v80, 0, v85
	v_mul_f32_e32 v85, v81, v81
	v_max_f32_e32 v81, 0, v86
	v_mul_f32_e32 v86, v82, v82
	v_max_f32_e32 v82, 0, v87
	v_max_f32_e32 v83, 0, v83
	v_mul_f32_e32 v84, v84, v84
	v_mul_f32_e32 v80, v80, v80
	v_mul_f32_e32 v81, v81, v81
	v_mul_f32_e32 v82, v82, v82
	v_mul_f32_e32 v83, v83, v83
	v_cvt_pk_bf16_f32 v80, v84, v80
	v_cvt_pk_bf16_f32 v81, v81, v82
	v_cvt_pk_bf16_f32 v82, v88, v85
	v_cvt_pk_bf16_f32 v83, v86, v83
	v_lshl_add_u64 v[84:85], v[148:149], 0, s[26:27]
	global_store_dwordx4 v[84:85], v[80:83], off sc1 nt
	s_nop 1
	ds_read_b32 v84, v157 offset:640
	v_lshl_add_u64 v[86:87], v[148:149], 0, s[28:29]
	s_waitcnt lgkmcnt(0)
	v_pk_mul_f32 v[90:91], v[8:9], v[84:85] op_sel_hi:[1,0]
	v_pk_mul_f32 v[80:81], v[14:15], v[84:85] op_sel_hi:[1,0]
	v_pk_mul_f32 v[82:83], v[12:13], v[84:85] op_sel_hi:[1,0]
	v_pk_mul_f32 v[88:89], v[10:11], v[84:85] op_sel_hi:[1,0]
	v_max_f32_e32 v85, 0, v90
	v_max_f32_e32 v82, 0, v82
	v_mul_f32_e32 v85, v85, v85
	v_max_f32_e32 v83, 0, v83
	v_max_f32_e32 v80, 0, v80
	v_mul_f32_e32 v82, v82, v82
	v_max_f32_e32 v90, 0, v91
	v_mul_f32_e32 v83, v83, v83
	v_max_f32_e32 v88, 0, v88
	v_mul_f32_e32 v91, v80, v80
	v_max_f32_e32 v80, 0, v81
	v_max_f32_e32 v81, 0, v89
	v_pk_mul_f32 v[74:75], v[74:75], v[84:85] op_sel_hi:[1,0]
	v_pk_mul_f32 v[72:73], v[72:73], v[84:85] op_sel_hi:[1,0]
	v_mul_f32_e32 v90, v90, v90
	v_mul_f32_e32 v88, v88, v88
	v_mul_f32_e32 v89, v80, v80
	v_mul_f32_e32 v92, v81, v81
	v_cvt_pk_bf16_f32 v80, v82, v83
	v_pk_mul_f32 v[78:79], v[78:79], v[84:85] op_sel_hi:[1,0]
	v_pk_mul_f32 v[76:77], v[76:77], v[84:85] op_sel_hi:[1,0]
	v_max_f32_e32 v72, 0, v72
	v_max_f32_e32 v73, 0, v73
	v_max_f32_e32 v74, 0, v74
	v_cvt_pk_bf16_f32 v81, v91, v89
	v_cvt_pk_bf16_f32 v82, v85, v90
	v_cvt_pk_bf16_f32 v83, v88, v92
	global_store_dwordx4 v[86:87], v[80:83], off sc1 nt
	s_nop 1
	v_max_f32_e32 v76, 0, v76
	v_mul_f32_e32 v80, v72, v72
	v_max_f32_e32 v72, 0, v77
	v_mul_f32_e32 v77, v73, v73
	v_max_f32_e32 v73, 0, v78
	v_mul_f32_e32 v78, v74, v74
	v_max_f32_e32 v74, 0, v79
	v_max_f32_e32 v75, 0, v75
	v_mul_f32_e32 v76, v76, v76
	v_mul_f32_e32 v72, v72, v72
	v_mul_f32_e32 v73, v73, v73
	v_mul_f32_e32 v74, v74, v74
	v_mul_f32_e32 v75, v75, v75
	v_cvt_pk_bf16_f32 v72, v76, v72
	v_cvt_pk_bf16_f32 v73, v73, v74
	v_cvt_pk_bf16_f32 v74, v80, v77
	v_cvt_pk_bf16_f32 v75, v78, v75
	v_lshl_add_u64 v[76:77], v[148:149], 0, s[30:31]
	global_store_dwordx4 v[76:77], v[72:75], off sc1 nt
	s_nop 1
	ds_read_b32 v76, v157 offset:704
	v_lshl_add_u64 v[78:79], v[148:149], 0, s[34:35]
	s_waitcnt lgkmcnt(0)
	v_pk_mul_f32 v[82:83], v[0:1], v[76:77] op_sel_hi:[1,0]
	v_pk_mul_f32 v[72:73], v[6:7], v[76:77] op_sel_hi:[1,0]
	v_pk_mul_f32 v[74:75], v[4:5], v[76:77] op_sel_hi:[1,0]
	v_pk_mul_f32 v[80:81], v[2:3], v[76:77] op_sel_hi:[1,0]
	v_max_f32_e32 v77, 0, v82
	v_max_f32_e32 v74, 0, v74
	v_mul_f32_e32 v77, v77, v77
	v_max_f32_e32 v75, 0, v75
	v_max_f32_e32 v72, 0, v72
	v_mul_f32_e32 v74, v74, v74
	v_max_f32_e32 v82, 0, v83
	v_mul_f32_e32 v75, v75, v75
	v_max_f32_e32 v80, 0, v80
	v_mul_f32_e32 v83, v72, v72
	v_max_f32_e32 v72, 0, v73
	v_max_f32_e32 v73, 0, v81
	v_pk_mul_f32 v[46:47], v[46:47], v[76:77] op_sel_hi:[1,0]
	v_pk_mul_f32 v[44:45], v[44:45], v[76:77] op_sel_hi:[1,0]
	v_mul_f32_e32 v82, v82, v82
	v_mul_f32_e32 v80, v80, v80
	v_mul_f32_e32 v81, v72, v72
	v_mul_f32_e32 v84, v73, v73
	v_cvt_pk_bf16_f32 v72, v74, v75
	v_pk_mul_f32 v[54:55], v[54:55], v[76:77] op_sel_hi:[1,0]
	v_pk_mul_f32 v[52:53], v[52:53], v[76:77] op_sel_hi:[1,0]
	v_max_f32_e32 v44, 0, v44
	v_max_f32_e32 v45, 0, v45
	v_max_f32_e32 v46, 0, v46
	v_cvt_pk_bf16_f32 v73, v83, v81
	v_cvt_pk_bf16_f32 v74, v77, v82
	v_cvt_pk_bf16_f32 v75, v80, v84
	global_store_dwordx4 v[78:79], v[72:75], off sc1 nt
	s_nop 1
	v_max_f32_e32 v52, 0, v52
	v_mul_f32_e32 v72, v44, v44
	v_max_f32_e32 v44, 0, v53
	v_mul_f32_e32 v53, v45, v45
	v_max_f32_e32 v45, 0, v54
	v_mul_f32_e32 v54, v46, v46
	v_max_f32_e32 v46, 0, v55
	v_max_f32_e32 v47, 0, v47
	v_mul_f32_e32 v52, v52, v52
	v_mul_f32_e32 v44, v44, v44
	v_mul_f32_e32 v45, v45, v45
	v_mul_f32_e32 v46, v46, v46
	v_mul_f32_e32 v47, v47, v47
	v_cvt_pk_bf16_f32 v44, v52, v44
	v_cvt_pk_bf16_f32 v45, v45, v46
	v_cvt_pk_bf16_f32 v46, v72, v53
	v_cvt_pk_bf16_f32 v47, v54, v47
	v_lshl_add_u64 v[52:53], v[148:149], 0, s[36:37]
	global_store_dwordx4 v[52:53], v[44:47], off sc1 nt
	s_nop 1
	s_cbranch_execz .LBB0_2797
	s_andn2_b64 vcc, exec, s[6:7]
	s_mov_b64 s[0:1], -1
	s_cbranch_vccnz .LBB0_2782
	s_branch .LBB0_2800

.LBB0_2862:
	s_waitcnt lgkmcnt(0)
	s_add_u32 s30, s14, 0x2b00000
	s_addc_u32 s31, s15, 0
	s_add_u32 s33, s14, 0xc400000
	s_addc_u32 s34, s15, 0
	s_add_i32 s4, s4, s5
	s_ashr_i32 s5, s4, 31
	s_lshr_b32 s5, s5, 27
	s_add_i32 s5, s4, s5
	s_ashr_i32 s6, s5, 5
	s_and_b32 s5, s5, 0xffe0
	s_waitcnt vmcnt(0)
	v_lshlrev_b32_e32 v0, 4, v170
	v_and_b32_e32 v1, 32, v170
	s_sub_i32 s5, s4, s5
	v_bfe_u32 v10, v170, 2, 4
	v_bitop3_b32 v8, v0, v1, 48 bitop3:0x6c
	v_and_b32_e32 v9, 64, v170
	v_lshrrev_b32_e32 v2, 3, v170
	s_movk_i32 s0, 0x70
	v_add_u32_e32 v11, 0x2000, v0
	s_bfe_i32 s4, s5, 0x80000
	v_or_b32_e32 v1, v8, v9
	v_and_or_b32 v3, v2, s0, v10
	v_lshrrev_b32_e32 v0, 7, v11
	s_movk_i32 s0, 0xf0
	s_bfe_u32 s4, s4, 0x3000c
	v_mul_u32_u24_e32 v172, 0x2100, v3
	v_add_u32_e32 v172, v172, v1
	v_and_or_b32 v3, v0, s0, v10
	s_add_i32 s7, s5, s4
	v_mul_u32_u24_e32 v174, 0x2100, v3
	v_add_u32_e32 v174, v174, v1
	v_lshrrev_b32_e32 v3, 1, v170
	v_lshrrev_b32_e32 v4, 5, v170
	s_bfe_i32 s4, s7, 0x80000
	s_and_b32 s7, s7, 0xf8
	v_and_b32_e32 v3, 24, v3
	v_and_b32_e32 v4, 4, v4
	v_bfe_u32 v5, v170, 2, 2
	s_sext_i32_i16 s4, s4
	s_sub_i32 s5, s5, s7
	v_or3_b32 v3, v4, v5, v3
	s_movk_i32 s0, 0x60
	s_lshl_b32 s6, s6, 3
	s_lshr_b32 s4, s4, 3
	s_sext_i32_i8 s5, s5
	s_lshr_b32 s1, s8, 6
	v_and_or_b32 v2, v2, s0, v3
	s_movk_i32 s0, 0xe0
	s_add_i32 s24, s6, s5
	s_bfe_i64 s[6:7], s[4:5], 0x100000
	v_and_or_b32 v0, v0, s0, v3
	s_lshr_b32 s0, s8, 8
	s_lshl_b32 s35, s1, 10
	s_lshl_b64 s[26:27], s[6:7], 21
	s_add_u32 s6, s30, s26
	s_addc_u32 s7, s31, s27
	s_add_i32 s36, s35, 0
	v_lshl_or_b32 v176, v2, 13, v1
	s_add_i32 m0, s36, 0x10000
	v_lshl_or_b32 v178, v0, 13, v1
	global_load_lds_dwordx4 v176, s[6:7]
	s_add_i32 m0, s36, 0x12000
	s_add_u32 s10, s6, 0x100000
	global_load_lds_dwordx4 v178, s[6:7]
	s_addc_u32 s11, s7, 0
	s_add_i32 m0, s36, 0x14000
	s_ashr_i32 s25, s24, 31
	global_load_lds_dwordx4 v176, s[10:11]
	s_add_i32 m0, s36, 0x16000
	v_mov_b32_e32 v177, 0
	global_load_lds_dwordx4 v178, s[10:11]
	s_mul_i32 s10, s24, 0x210000
	s_mov_b32 s11, 0
	s_add_u32 s16, s33, s10
	s_addc_u32 s17, s34, s11
	s_add_i32 s37, s36, 0x2000
	s_mov_b32 m0, s36
	s_add_u32 s10, s16, 0x108000
	global_load_lds_dwordx4 v172, s[16:17]
	s_mov_b32 m0, s37
	s_addc_u32 s11, s17, 0
	s_add_i32 s38, s36, 0x4000
	global_load_lds_dwordx4 v174, s[16:17]
	s_mov_b32 m0, s38
	s_add_i32 s39, s36, 0x6000
	global_load_lds_dwordx4 v172, s[10:11]
	s_mov_b32 m0, s39
	v_mov_b32_e32 v179, v177
	global_load_lds_dwordx4 v174, s[10:11]
	v_mov_b32_e32 v173, v177
	v_mov_b32_e32 v175, v177
	s_cmp_eq_u32 s0, 1
	s_mov_b32 s5, 0
	v_lshl_add_u64 v[6:7], s[6:7], 0, v[176:177]
	v_lshl_add_u64 v[4:5], s[6:7], 0, v[178:179]
	v_lshl_add_u64 v[0:1], s[16:17], 0, v[172:173]
	s_cselect_b64 s[10:11], -1, 0
	s_cmp_lg_u32 s0, 1
	v_lshl_add_u64 v[2:3], s[16:17], 0, v[174:175]
	s_cbranch_scc1 .LBB0_2864
	s_barrier
.LBB0_2864:
	s_add_u32 s16, s14, 0x412a000
	s_mov_b64 s[18:19], 0x80
	s_addc_u32 s17, s15, 0
	s_and_b32 s40, s1, 3
	s_add_i32 m0, s36, 0x18000
	v_lshl_add_u64 v[6:7], v[6:7], 0, s[18:19]
	s_lshl_b32 s1, s0, 13
	s_lshl_b32 s9, s40, 12
	s_waitcnt vmcnt(2)
	s_barrier
	global_load_lds_dwordx4 v[6:7], off
	v_lshl_add_u64 v[4:5], v[4:5], 0, s[18:19]
	s_add_i32 m0, s36, 0x1a000
	s_add_i32 s41, s36, 0x8000
	s_add_i32 s42, s36, 0xa000
	global_load_lds_dwordx4 v[4:5], off
	v_lshl_add_u64 v[0:1], v[0:1], 0, s[18:19]
	s_mov_b32 m0, s41
	s_add_u32 s6, s6, 0x100080
	global_load_lds_dwordx4 v[0:1], off
	v_lshl_add_u64 v[0:1], v[2:3], 0, s[18:19]
	s_mov_b32 m0, s42
	s_addc_u32 s7, s7, 0
	global_load_lds_dwordx4 v[0:1], off
	s_add_i32 m0, s36, 0x1c000
	v_lshl_add_u64 v[0:1], s[6:7], 0, v[176:177]
	global_load_lds_dwordx4 v[0:1], off
	v_lshl_add_u64 v[0:1], s[6:7], 0, v[178:179]
	s_add_i32 m0, s36, 0x1e000
	v_lshlrev_b32_e32 v4, 2, v170
	global_load_lds_dwordx4 v[0:1], off
	v_bfe_u32 v0, v170, 4, 2
	v_and_b32_e32 v1, 15, v170
	v_lshlrev_b32_e32 v3, 4, v0
	v_lshl_or_b32 v169, s0, 6, v1
	v_lshlrev_b32_e32 v2, 3, v0
	v_lshl_or_b32 v1, v1, 6, v3
	v_and_b32_e32 v4, 32, v4
	v_cmp_eq_u32_e64 s[6:7], 0, v0
	v_lshlrev_b32_e32 v0, 6, v11
	v_bitop3_b32 v5, v1, s1, v4 bitop3:0xde
	v_lshlrev_b32_e32 v1, 6, v170
	s_movk_i32 s0, 0x3c0
	v_lshl_or_b32 v211, s40, 5, v2
	v_and_b32_e32 v0, 0x1e0000, v0
	v_lshlrev_b32_e32 v2, 13, v10
	v_and_or_b32 v1, v1, s0, v3
	v_or3_b32 v0, v8, v0, v2
	v_bitop3_b32 v210, s9, v1, v4 bitop3:0xf6
	v_mov_b32_e32 v0, v174
	v_mov_b32_e32 v1, v177
	v_lshl_add_u64 v[0:1], s[14:15], 0, v[0:1]
	s_mov_b64 s[0:1], 0xc508080
	v_lshl_add_u64 v[180:181], v[0:1], 0, s[0:1]
	v_lshlrev_b32_e32 v0, 10, v170
	v_and_b32_e32 v0, 0xe0000, v0
	v_or3_b32 v0, v8, v0, v2
	s_cmpk_lt_u32 s8, 0x100
	v_mov_b32_e32 v0, v172
	v_mov_b32_e32 v1, v177
	s_waitcnt vmcnt(6)
	s_cselect_b64 s[20:21], -1, 0
	v_lshl_add_u64 v[0:1], s[14:15], 0, v[0:1]
	s_add_u32 s43, s14, 0x2b00100
	v_lshl_add_u64 v[170:171], v[0:1], 0, s[0:1]
	s_addc_u32 s44, s15, 0
	s_add_i32 s46, 0, 0x10000
	s_add_i32 s47, 0, 0x14000
	v_mbcnt_lo_u32_b32 v0, -1, 0
	s_sext_i32_i8 s45, s4
	v_mov_b64_e32 v[182:183], 0x200
	v_mov_b64_e32 v[184:185], 0x1ff
	v_add_u32_e32 v212, s46, v210
	v_add_u32_e32 v213, s47, v210
	v_add_u32_e32 v214, 0, v5
	s_mov_b64 s[14:15], 0x100
	v_mbcnt_hi_u32_b32 v215, -1, v0
	s_mov_b32 s48, 0
	s_barrier
	s_branch .LBB0_2867

.LBB0_2873:
	s_ashr_i32 s1, s0, 31
	s_lshl_b64 s[22:23], s[0:1], 21
	s_add_u32 s0, s30, s22
	s_addc_u32 s1, s31, s23
	s_ashr_i32 s25, s24, 31
	s_mul_i32 s28, s24, 0x210000
	s_mov_b32 s29, 0
	s_add_u32 s25, s43, s26
	v_mov_b32_e32 v0, 0
	v_lshl_add_u64 v[128:129], v[180:181], 0, s[28:29]
	v_lshl_add_u64 v[130:131], v[170:171], 0, s[28:29]
	s_addc_u32 s52, s44, s27
	s_mov_b32 s53, 0
	s_mov_b64 s[26:27], 0
	s_waitcnt lgkmcnt(0)
	v_mov_b32_e32 v1, v0
	v_mov_b32_e32 v2, v0
	v_mov_b32_e32 v3, v0
	v_mov_b32_e32 v4, v0
	v_mov_b32_e32 v5, v0
	v_mov_b32_e32 v6, v0
	v_mov_b32_e32 v7, v0
	v_mov_b32_e32 v16, v0
	v_mov_b32_e32 v17, v0
	v_mov_b32_e32 v18, v0
	v_mov_b32_e32 v19, v0
	v_mov_b32_e32 v20, v0
	v_mov_b32_e32 v21, v0
	v_mov_b32_e32 v22, v0
	v_mov_b32_e32 v23, v0
	v_mov_b32_e32 v32, v0
	v_mov_b32_e32 v33, v0
	v_mov_b32_e32 v34, v0
	v_mov_b32_e32 v35, v0
	v_mov_b32_e32 v36, v0
	v_mov_b32_e32 v37, v0
	v_mov_b32_e32 v38, v0
	v_mov_b32_e32 v39, v0
	v_mov_b32_e32 v48, v0
	v_mov_b32_e32 v49, v0
	v_mov_b32_e32 v50, v0
	v_mov_b32_e32 v51, v0
	v_mov_b32_e32 v52, v0
	v_mov_b32_e32 v53, v0
	v_mov_b32_e32 v54, v0
	v_mov_b32_e32 v55, v0
	v_mov_b32_e32 v8, v0
	v_mov_b32_e32 v9, v0
	v_mov_b32_e32 v10, v0
	v_mov_b32_e32 v11, v0
	v_mov_b32_e32 v12, v0
	v_mov_b32_e32 v13, v0
	v_mov_b32_e32 v14, v0
	v_mov_b32_e32 v15, v0
	v_mov_b32_e32 v24, v0
	v_mov_b32_e32 v25, v0
	v_mov_b32_e32 v26, v0
	v_mov_b32_e32 v27, v0
	v_mov_b32_e32 v28, v0
	v_mov_b32_e32 v29, v0
	v_mov_b32_e32 v30, v0
	v_mov_b32_e32 v31, v0
	v_mov_b32_e32 v40, v0
	v_mov_b32_e32 v41, v0
	v_mov_b32_e32 v42, v0
	v_mov_b32_e32 v43, v0
	v_mov_b32_e32 v44, v0
	v_mov_b32_e32 v45, v0
	v_mov_b32_e32 v46, v0
	v_mov_b32_e32 v47, v0
	v_mov_b32_e32 v56, v0
	v_mov_b32_e32 v57, v0
	v_mov_b32_e32 v58, v0
	v_mov_b32_e32 v59, v0
	v_mov_b32_e32 v60, v0
	v_mov_b32_e32 v61, v0
	v_mov_b32_e32 v62, v0
	v_mov_b32_e32 v63, v0
	v_mov_b32_e32 v64, v0
	v_mov_b32_e32 v65, v0
	v_mov_b32_e32 v66, v0
	v_mov_b32_e32 v67, v0
	v_mov_b32_e32 v68, v0
	v_mov_b32_e32 v69, v0
	v_mov_b32_e32 v70, v0
	v_mov_b32_e32 v71, v0
	v_mov_b32_e32 v80, v0
	v_mov_b32_e32 v81, v0
	v_mov_b32_e32 v82, v0
	v_mov_b32_e32 v83, v0
	v_mov_b32_e32 v84, v0
	v_mov_b32_e32 v85, v0
	v_mov_b32_e32 v86, v0
	v_mov_b32_e32 v87, v0
	v_mov_b32_e32 v96, v0
	v_mov_b32_e32 v97, v0
	v_mov_b32_e32 v98, v0
	v_mov_b32_e32 v99, v0
	v_mov_b32_e32 v100, v0
	v_mov_b32_e32 v101, v0
	v_mov_b32_e32 v102, v0
	v_mov_b32_e32 v103, v0
	v_mov_b32_e32 v112, v0
	v_mov_b32_e32 v113, v0
	v_mov_b32_e32 v114, v0
	v_mov_b32_e32 v115, v0
	v_mov_b32_e32 v116, v0
	v_mov_b32_e32 v117, v0
	v_mov_b32_e32 v118, v0
	v_mov_b32_e32 v119, v0
	v_mov_b32_e32 v72, v0
	v_mov_b32_e32 v73, v0
	v_mov_b32_e32 v74, v0
	v_mov_b32_e32 v75, v0
	v_mov_b32_e32 v76, v0
	v_mov_b32_e32 v77, v0
	v_mov_b32_e32 v78, v0
	v_mov_b32_e32 v79, v0
	v_mov_b32_e32 v88, v0
	v_mov_b32_e32 v89, v0
	v_mov_b32_e32 v90, v0
	v_mov_b32_e32 v91, v0
	v_mov_b32_e32 v92, v0
	v_mov_b32_e32 v93, v0
	v_mov_b32_e32 v94, v0
	v_mov_b32_e32 v95, v0
	v_mov_b32_e32 v104, v0
	v_mov_b32_e32 v105, v0
	v_mov_b32_e32 v106, v0
	v_mov_b32_e32 v107, v0
	v_mov_b32_e32 v108, v0
	v_mov_b32_e32 v109, v0
	v_mov_b32_e32 v110, v0
	v_mov_b32_e32 v111, v0
	v_mov_b32_e32 v120, v0
	v_mov_b32_e32 v121, v0
	v_mov_b32_e32 v122, v0
	v_mov_b32_e32 v123, v0
	v_mov_b32_e32 v124, v0
	v_mov_b32_e32 v125, v0
	v_mov_b32_e32 v126, v0
	v_mov_b32_e32 v127, v0
.LBB0_2874:
	ds_read_b128 v[132:135], v212
	ds_read_b128 v[136:139], v212 offset:1024
	ds_read_b128 v[140:143], v212 offset:2048
	ds_read_b128 v[144:147], v212 offset:3072
	ds_read_b128 v[148:151], v213
	ds_read_b128 v[152:155], v213 offset:1024
	ds_read_b128 v[156:159], v213 offset:2048
	ds_read_b128 v[160:163], v213 offset:3072
	s_add_i32 s54, s53, 2
	s_add_u32 s4, s25, s26
	s_addc_u32 s28, s52, s27
	s_cmpk_eq_i32 s26, 0x1f00
	s_cselect_b32 s29, s1, s28
	s_cselect_b32 s28, s0, s4
	s_cselect_b32 s4, 0, s54
	s_cselect_b32 s56, s51, s24
	v_lshl_add_u64 v[220:221], v[130:131], 0, s[26:27]
	s_add_i32 m0, s36, 0xc000
	ds_read_b128 v[164:167], v214
	ds_read_b128 v[186:189], v214 offset:1024
	ds_read_b128 v[190:193], v214 offset:2048
	ds_read_b128 v[194:197], v214 offset:3072
	ds_read_b128 v[198:201], v214 offset:4096
	ds_read_b128 v[202:205], v214 offset:5120
	ds_read_b128 v[206:209], v214 offset:6144
	ds_read_b128 v[216:219], v214 offset:7168
	global_load_lds_dwordx4 v[220:221], off
	v_lshl_add_u64 v[220:221], v[128:129], 0, s[26:27]
	s_add_i32 m0, s36, 0xe000
	s_nop 0
	global_load_lds_dwordx4 v[220:221], off
	s_waitcnt vmcnt(8)
	s_waitcnt lgkmcnt(0)
	s_barrier
	s_setprio 1
	s_waitcnt lgkmcnt(0)
	v_mfma_f32_16x16x32_bf16 v[124:127], v[132:135], v[164:167], v[124:127]
	v_mfma_f32_16x16x32_bf16 v[120:123], v[140:143], v[164:167], v[120:123]
	v_mfma_f32_16x16x32_bf16 v[108:111], v[132:135], v[190:193], v[108:111]
	v_mfma_f32_16x16x32_bf16 v[104:107], v[140:143], v[190:193], v[104:107]
	v_mfma_f32_16x16x32_bf16 v[92:95], v[132:135], v[198:201], v[92:95]
	v_mfma_f32_16x16x32_bf16 v[88:91], v[140:143], v[198:201], v[88:91]
	v_mfma_f32_16x16x32_bf16 v[76:79], v[132:135], v[206:209], v[76:79]
	v_mfma_f32_16x16x32_bf16 v[72:75], v[140:143], v[206:209], v[72:75]
	v_mfma_f32_16x16x32_bf16 v[124:127], v[136:139], v[186:189], v[124:127]
	v_mfma_f32_16x16x32_bf16 v[120:123], v[144:147], v[186:189], v[120:123]
	v_mfma_f32_16x16x32_bf16 v[108:111], v[136:139], v[194:197], v[108:111]
	v_mfma_f32_16x16x32_bf16 v[104:107], v[144:147], v[194:197], v[104:107]
	v_mfma_f32_16x16x32_bf16 v[92:95], v[136:139], v[202:205], v[92:95]
	v_mfma_f32_16x16x32_bf16 v[88:91], v[144:147], v[202:205], v[88:91]
	v_mfma_f32_16x16x32_bf16 v[76:79], v[136:139], v[216:219], v[76:79]
	v_mfma_f32_16x16x32_bf16 v[72:75], v[144:147], v[216:219], v[72:75]
	s_setprio 0
	s_setprio 1
	v_mfma_f32_16x16x32_bf16 v[116:119], v[148:151], v[164:167], v[116:119]
	v_mfma_f32_16x16x32_bf16 v[112:115], v[156:159], v[164:167], v[112:115]
	v_mfma_f32_16x16x32_bf16 v[100:103], v[148:151], v[190:193], v[100:103]
	v_mfma_f32_16x16x32_bf16 v[96:99], v[156:159], v[190:193], v[96:99]
	v_mfma_f32_16x16x32_bf16 v[84:87], v[148:151], v[198:201], v[84:87]
	v_mfma_f32_16x16x32_bf16 v[80:83], v[156:159], v[198:201], v[80:83]
	v_mfma_f32_16x16x32_bf16 v[68:71], v[148:151], v[206:209], v[68:71]
	v_mfma_f32_16x16x32_bf16 v[64:67], v[156:159], v[206:209], v[64:67]
	v_mfma_f32_16x16x32_bf16 v[116:119], v[152:155], v[186:189], v[116:119]
	v_mfma_f32_16x16x32_bf16 v[112:115], v[160:163], v[186:189], v[112:115]
	v_mfma_f32_16x16x32_bf16 v[100:103], v[152:155], v[194:197], v[100:103]
	v_mfma_f32_16x16x32_bf16 v[96:99], v[160:163], v[194:197], v[96:99]
	v_mfma_f32_16x16x32_bf16 v[84:87], v[152:155], v[202:205], v[84:87]
	v_mfma_f32_16x16x32_bf16 v[80:83], v[160:163], v[202:205], v[80:83]
	v_mfma_f32_16x16x32_bf16 v[68:71], v[152:155], v[216:219], v[68:71]
	v_mfma_f32_16x16x32_bf16 v[64:67], v[160:163], v[216:219], v[64:67]
	s_setprio 0
	s_barrier
	s_add_i32 s55, s46, s35
	v_lshl_add_u64 v[220:221], s[28:29], 0, v[176:177]
	s_mov_b32 m0, s55
	ds_read_b128 v[164:167], v214 offset:16384
	ds_read_b128 v[186:189], v214 offset:17408
	ds_read_b128 v[190:193], v214 offset:18432
	ds_read_b128 v[194:197], v214 offset:19456
	ds_read_b128 v[198:201], v214 offset:20480
	ds_read_b128 v[202:205], v214 offset:21504
	ds_read_b128 v[206:209], v214 offset:22528
	ds_read_b128 v[216:219], v214 offset:23552
	global_load_lds_dwordx4 v[220:221], off
	s_add_i32 m0, s55, 0x2000
	s_add_u32 s58, s28, 0x100000
	v_lshl_add_u64 v[222:223], s[28:29], 0, v[178:179]
	s_addc_u32 s59, s29, 0
	s_add_i32 s55, s47, s35
	global_load_lds_dwordx4 v[222:223], off
	v_lshl_add_u64 v[224:225], s[58:59], 0, v[176:177]
	s_mov_b32 m0, s55
	s_ashr_i32 s57, s56, 31
	global_load_lds_dwordx4 v[224:225], off
	s_add_i32 m0, s55, 0x2000
	s_mul_i32 s56, s56, 0x210000
	s_mov_b32 s57, 0
	s_add_u32 s55, s33, s56
	v_lshl_add_u64 v[224:225], s[58:59], 0, v[178:179]
	s_addc_u32 s58, s34, s57
	s_lshl_b64 s[56:57], s[4:5], 7
	s_add_u32 s56, s55, s56
	s_addc_u32 s57, s58, s57
	global_load_lds_dwordx4 v[224:225], off
	v_lshl_add_u64 v[224:225], s[56:57], 0, v[172:173]
	s_mov_b32 m0, s36
	s_nop 0
	global_load_lds_dwordx4 v[224:225], off
	v_lshl_add_u64 v[224:225], s[56:57], 0, v[174:175]
	s_mov_b32 m0, s37
	s_nop 0
	global_load_lds_dwordx4 v[224:225], off
	s_waitcnt vmcnt(8)
	s_waitcnt lgkmcnt(0)
	s_barrier
	s_setprio 1
	s_waitcnt lgkmcnt(0)
	v_mfma_f32_16x16x32_bf16 v[60:63], v[132:135], v[164:167], v[60:63]
	v_mfma_f32_16x16x32_bf16 v[56:59], v[140:143], v[164:167], v[56:59]
	v_mfma_f32_16x16x32_bf16 v[44:47], v[132:135], v[190:193], v[44:47]
	v_mfma_f32_16x16x32_bf16 v[40:43], v[140:143], v[190:193], v[40:43]
	v_mfma_f32_16x16x32_bf16 v[28:31], v[132:135], v[198:201], v[28:31]
	v_mfma_f32_16x16x32_bf16 v[24:27], v[140:143], v[198:201], v[24:27]
	v_mfma_f32_16x16x32_bf16 v[12:15], v[132:135], v[206:209], v[12:15]
	v_mfma_f32_16x16x32_bf16 v[8:11], v[140:143], v[206:209], v[8:11]
	v_mfma_f32_16x16x32_bf16 v[60:63], v[136:139], v[186:189], v[60:63]
	v_mfma_f32_16x16x32_bf16 v[56:59], v[144:147], v[186:189], v[56:59]
	v_mfma_f32_16x16x32_bf16 v[44:47], v[136:139], v[194:197], v[44:47]
	v_mfma_f32_16x16x32_bf16 v[40:43], v[144:147], v[194:197], v[40:43]
	v_mfma_f32_16x16x32_bf16 v[28:31], v[136:139], v[202:205], v[28:31]
	v_mfma_f32_16x16x32_bf16 v[24:27], v[144:147], v[202:205], v[24:27]
	v_mfma_f32_16x16x32_bf16 v[12:15], v[136:139], v[216:219], v[12:15]
	v_mfma_f32_16x16x32_bf16 v[8:11], v[144:147], v[216:219], v[8:11]
	s_setprio 0
	s_setprio 1
	v_mfma_f32_16x16x32_bf16 v[52:55], v[148:151], v[164:167], v[52:55]
	v_mfma_f32_16x16x32_bf16 v[48:51], v[156:159], v[164:167], v[48:51]
	v_mfma_f32_16x16x32_bf16 v[36:39], v[148:151], v[190:193], v[36:39]
	v_mfma_f32_16x16x32_bf16 v[32:35], v[156:159], v[190:193], v[32:35]
	v_mfma_f32_16x16x32_bf16 v[20:23], v[148:151], v[198:201], v[20:23]
	v_mfma_f32_16x16x32_bf16 v[16:19], v[156:159], v[198:201], v[16:19]
	v_mfma_f32_16x16x32_bf16 v[4:7], v[148:151], v[206:209], v[4:7]
	v_mfma_f32_16x16x32_bf16 v[0:3], v[156:159], v[206:209], v[0:3]
	v_mfma_f32_16x16x32_bf16 v[52:55], v[152:155], v[186:189], v[52:55]
	v_mfma_f32_16x16x32_bf16 v[48:51], v[160:163], v[186:189], v[48:51]
	v_mfma_f32_16x16x32_bf16 v[36:39], v[152:155], v[194:197], v[36:39]
	v_mfma_f32_16x16x32_bf16 v[32:35], v[160:163], v[194:197], v[32:35]
	v_mfma_f32_16x16x32_bf16 v[20:23], v[152:155], v[202:205], v[20:23]
	v_mfma_f32_16x16x32_bf16 v[16:19], v[160:163], v[202:205], v[16:19]
	v_mfma_f32_16x16x32_bf16 v[4:7], v[152:155], v[216:219], v[4:7]
	v_mfma_f32_16x16x32_bf16 v[0:3], v[160:163], v[216:219], v[0:3]
	s_setprio 0
	s_barrier
	s_add_i32 s59, 0, 0x18000
	s_add_i32 s60, 0, 0x1c000
	v_add_u32_e32 v144, s59, v210
	v_add_u32_e32 v160, s60, v210
	ds_read_b128 v[132:135], v144
	ds_read_b128 v[136:139], v144 offset:1024
	ds_read_b128 v[140:143], v144 offset:2048
	ds_read_b128 v[144:147], v144 offset:3072
	ds_read_b128 v[148:151], v160
	ds_read_b128 v[152:155], v160 offset:1024
	ds_read_b128 v[156:159], v160 offset:2048
	ds_read_b128 v[160:163], v160 offset:3072
	s_add_u32 s56, s56, 0x108000
	s_addc_u32 s57, s57, 0
	s_mov_b32 m0, s38
	v_lshl_add_u64 v[224:225], s[56:57], 0, v[172:173]
	ds_read_b128 v[164:167], v214 offset:32768
	ds_read_b128 v[186:189], v214 offset:33792
	ds_read_b128 v[190:193], v214 offset:34816
	ds_read_b128 v[194:197], v214 offset:35840
	ds_read_b128 v[198:201], v214 offset:36864
	ds_read_b128 v[202:205], v214 offset:37888
	ds_read_b128 v[206:209], v214 offset:38912
	ds_read_b128 v[216:219], v214 offset:39936
	global_load_lds_dwordx4 v[224:225], off
	v_lshl_add_u64 v[224:225], s[56:57], 0, v[174:175]
	s_mov_b32 m0, s39
	s_nop 0
	global_load_lds_dwordx4 v[224:225], off
	s_waitcnt vmcnt(8)
	s_waitcnt lgkmcnt(0)
	s_barrier
	s_setprio 1
	s_waitcnt lgkmcnt(0)
	v_mfma_f32_16x16x32_bf16 v[124:127], v[132:135], v[164:167], v[124:127]
	v_mfma_f32_16x16x32_bf16 v[120:123], v[140:143], v[164:167], v[120:123]
	v_mfma_f32_16x16x32_bf16 v[108:111], v[132:135], v[190:193], v[108:111]
	v_mfma_f32_16x16x32_bf16 v[104:107], v[140:143], v[190:193], v[104:107]
	v_mfma_f32_16x16x32_bf16 v[92:95], v[132:135], v[198:201], v[92:95]
	v_mfma_f32_16x16x32_bf16 v[88:91], v[140:143], v[198:201], v[88:91]
	v_mfma_f32_16x16x32_bf16 v[76:79], v[132:135], v[206:209], v[76:79]
	v_mfma_f32_16x16x32_bf16 v[72:75], v[140:143], v[206:209], v[72:75]
	v_mfma_f32_16x16x32_bf16 v[124:127], v[136:139], v[186:189], v[124:127]
	v_mfma_f32_16x16x32_bf16 v[120:123], v[144:147], v[186:189], v[120:123]
	v_mfma_f32_16x16x32_bf16 v[108:111], v[136:139], v[194:197], v[108:111]
	v_mfma_f32_16x16x32_bf16 v[104:107], v[144:147], v[194:197], v[104:107]
	v_mfma_f32_16x16x32_bf16 v[92:95], v[136:139], v[202:205], v[92:95]
	v_mfma_f32_16x16x32_bf16 v[88:91], v[144:147], v[202:205], v[88:91]
	v_mfma_f32_16x16x32_bf16 v[76:79], v[136:139], v[216:219], v[76:79]
	v_mfma_f32_16x16x32_bf16 v[72:75], v[144:147], v[216:219], v[72:75]
	s_setprio 0
	s_setprio 1
	v_mfma_f32_16x16x32_bf16 v[116:119], v[148:151], v[164:167], v[116:119]
	v_mfma_f32_16x16x32_bf16 v[112:115], v[156:159], v[164:167], v[112:115]
	v_mfma_f32_16x16x32_bf16 v[100:103], v[148:151], v[190:193], v[100:103]
	v_mfma_f32_16x16x32_bf16 v[96:99], v[156:159], v[190:193], v[96:99]
	v_mfma_f32_16x16x32_bf16 v[84:87], v[148:151], v[198:201], v[84:87]
	v_mfma_f32_16x16x32_bf16 v[80:83], v[156:159], v[198:201], v[80:83]
	v_mfma_f32_16x16x32_bf16 v[68:71], v[148:151], v[206:209], v[68:71]
	v_mfma_f32_16x16x32_bf16 v[64:67], v[156:159], v[206:209], v[64:67]
	v_mfma_f32_16x16x32_bf16 v[116:119], v[152:155], v[186:189], v[116:119]
	v_mfma_f32_16x16x32_bf16 v[112:115], v[160:163], v[186:189], v[112:115]
	v_mfma_f32_16x16x32_bf16 v[100:103], v[152:155], v[194:197], v[100:103]
	v_mfma_f32_16x16x32_bf16 v[96:99], v[160:163], v[194:197], v[96:99]
	v_mfma_f32_16x16x32_bf16 v[84:87], v[152:155], v[202:205], v[84:87]
	v_mfma_f32_16x16x32_bf16 v[80:83], v[160:163], v[202:205], v[80:83]
	v_mfma_f32_16x16x32_bf16 v[68:71], v[152:155], v[216:219], v[68:71]
	v_mfma_f32_16x16x32_bf16 v[64:67], v[160:163], v[216:219], v[64:67]
	s_setprio 0
	s_barrier
	s_add_i32 s56, s59, s35
	v_lshl_add_u64 v[220:221], v[220:221], 0, s[18:19]
	s_mov_b32 m0, s56
	ds_read_b128 v[164:167], v214 offset:49152
	ds_read_b128 v[186:189], v214 offset:50176
	ds_read_b128 v[190:193], v214 offset:51200
	ds_read_b128 v[194:197], v214 offset:52224
	ds_read_b128 v[198:201], v214 offset:53248
	ds_read_b128 v[202:205], v214 offset:54272
	ds_read_b128 v[206:209], v214 offset:55296
	ds_read_b128 v[216:219], v214 offset:56320
	global_load_lds_dwordx4 v[220:221], off
	s_add_i32 m0, s56, 0x2000
	s_add_u32 s28, s28, 0x100080
	v_lshl_add_u64 v[220:221], v[222:223], 0, s[18:19]
	s_addc_u32 s29, s29, 0
	s_add_i32 s56, s60, s35
	global_load_lds_dwordx4 v[220:221], off
	v_lshl_add_u64 v[220:221], s[28:29], 0, v[176:177]
	s_mov_b32 m0, s56
	s_or_b32 s4, s4, 1
	global_load_lds_dwordx4 v[220:221], off
	v_lshl_add_u64 v[220:221], s[28:29], 0, v[178:179]
	s_add_i32 m0, s56, 0x2000
	s_lshl_b64 s[28:29], s[4:5], 7
	s_add_u32 s28, s55, s28
	s_addc_u32 s29, s58, s29
	global_load_lds_dwordx4 v[220:221], off
	v_lshl_add_u64 v[220:221], s[28:29], 0, v[172:173]
	s_mov_b32 m0, s41
	s_nop 0
	global_load_lds_dwordx4 v[220:221], off
	v_lshl_add_u64 v[220:221], s[28:29], 0, v[174:175]
	s_mov_b32 m0, s42
	s_nop 0
	global_load_lds_dwordx4 v[220:221], off
	s_waitcnt vmcnt(8)
	s_waitcnt lgkmcnt(0)
	s_barrier
	s_setprio 1
	s_waitcnt lgkmcnt(0)
	v_mfma_f32_16x16x32_bf16 v[60:63], v[132:135], v[164:167], v[60:63]
	v_mfma_f32_16x16x32_bf16 v[56:59], v[140:143], v[164:167], v[56:59]
	v_mfma_f32_16x16x32_bf16 v[44:47], v[132:135], v[190:193], v[44:47]
	v_mfma_f32_16x16x32_bf16 v[40:43], v[140:143], v[190:193], v[40:43]
	v_mfma_f32_16x16x32_bf16 v[28:31], v[132:135], v[198:201], v[28:31]
	v_mfma_f32_16x16x32_bf16 v[24:27], v[140:143], v[198:201], v[24:27]
	v_mfma_f32_16x16x32_bf16 v[12:15], v[132:135], v[206:209], v[12:15]
	v_mfma_f32_16x16x32_bf16 v[8:11], v[140:143], v[206:209], v[8:11]
	v_mfma_f32_16x16x32_bf16 v[60:63], v[136:139], v[186:189], v[60:63]
	v_mfma_f32_16x16x32_bf16 v[56:59], v[144:147], v[186:189], v[56:59]
	v_mfma_f32_16x16x32_bf16 v[44:47], v[136:139], v[194:197], v[44:47]
	v_mfma_f32_16x16x32_bf16 v[40:43], v[144:147], v[194:197], v[40:43]
	v_mfma_f32_16x16x32_bf16 v[28:31], v[136:139], v[202:205], v[28:31]
	v_mfma_f32_16x16x32_bf16 v[24:27], v[144:147], v[202:205], v[24:27]
	v_mfma_f32_16x16x32_bf16 v[12:15], v[136:139], v[216:219], v[12:15]
	v_mfma_f32_16x16x32_bf16 v[8:11], v[144:147], v[216:219], v[8:11]
	s_setprio 0
	s_setprio 1
	v_mfma_f32_16x16x32_bf16 v[52:55], v[148:151], v[164:167], v[52:55]
	v_mfma_f32_16x16x32_bf16 v[48:51], v[156:159], v[164:167], v[48:51]
	v_mfma_f32_16x16x32_bf16 v[36:39], v[148:151], v[190:193], v[36:39]
	v_mfma_f32_16x16x32_bf16 v[32:35], v[156:159], v[190:193], v[32:35]
	v_mfma_f32_16x16x32_bf16 v[20:23], v[148:151], v[198:201], v[20:23]
	v_mfma_f32_16x16x32_bf16 v[16:19], v[156:159], v[198:201], v[16:19]
	v_mfma_f32_16x16x32_bf16 v[4:7], v[148:151], v[206:209], v[4:7]
	v_mfma_f32_16x16x32_bf16 v[0:3], v[156:159], v[206:209], v[0:3]
	v_mfma_f32_16x16x32_bf16 v[52:55], v[152:155], v[186:189], v[52:55]
	v_mfma_f32_16x16x32_bf16 v[48:51], v[160:163], v[186:189], v[48:51]
	v_mfma_f32_16x16x32_bf16 v[36:39], v[152:155], v[194:197], v[36:39]
	v_mfma_f32_16x16x32_bf16 v[32:35], v[160:163], v[194:197], v[32:35]
	v_mfma_f32_16x16x32_bf16 v[20:23], v[152:155], v[202:205], v[20:23]
	v_mfma_f32_16x16x32_bf16 v[16:19], v[160:163], v[202:205], v[16:19]
	v_mfma_f32_16x16x32_bf16 v[4:7], v[152:155], v[216:219], v[4:7]
	v_mfma_f32_16x16x32_bf16 v[0:3], v[160:163], v[216:219], v[0:3]
	s_setprio 0
	s_barrier
	s_add_u32 s26, s26, 0x100
	s_addc_u32 s27, s27, 0
	s_cmp_gt_u32 s53, 61
	s_mov_b32 s53, s54
	s_cbranch_scc0 .LBB0_2874
	s_and_b64 vcc, exec, s[20:21]
	s_cbranch_vccz .LBB0_2877
	s_barrier
